# hoist ssq loads in QKV/DQ/KVUP/UQ epilogues too
# speedup vs baseline: 1.0133x; 1.0077x over previous
.LBB0_355:
	v_lshl_add_u32 v148, s6, 8, v150
	v_ashrrev_i32_e32 v149, 31, v148
	v_lshl_add_u64 v[156:157], v[148:149], 2, s[14:15]
	global_load_dword v232, v[156:157], off offset:64
	global_load_dword v233, v[156:157], off offset:128
	global_load_dword v234, v[156:157], off offset:192
	global_load_dword v235, v[156:157], off offset:512
	global_load_dword v236, v[156:157], off offset:576
	global_load_dword v237, v[156:157], off offset:640
	global_load_dword v238, v[156:157], off offset:704
	global_load_dword v157, v[156:157], off
	s_ashr_i32 s6, s10, 2
	v_lshlrev_b64 v[158:159], 11, v[148:149]
	s_ashr_i32 s7, s6, 31
	s_lshl_b64 s[48:49], s[6:7], 26
	s_cmp_lt_u32 s10, 4
	s_cselect_b64 s[6:7], -1, 0
	s_add_u32 s48, s61, s48
	s_addc_u32 s49, s62, s49
	s_lshl_b32 s10, s10, 9
	v_lshl_add_u64 v[158:159], s[48:49], 0, v[158:159]
	s_and_b32 s10, s10, 0x600
	v_or_b32_e32 v156, 16, v148
	v_lshl_add_u64 v[158:159], v[158:159], 0, s[10:11]
	s_andn2_b64 vcc, exec, s[4:5]
	s_mov_b64 s[4:5], -1
	s_waitcnt vmcnt(0)
	v_fmamk_f32 v149, v157, 0x3a800000, v155
	v_rsq_f32_e32 v149, v149
	v_ashrrev_i32_e32 v157, 31, v156
	v_mul_f32_e32 v162, 0x3e38aa3b, v149
	v_cndmask_b32_e64 v162, v149, v162, s[6:7]
	v_pk_mul_f32 v[128:129], v[128:129], v[162:163] op_sel_hi:[1,0]
	v_pk_mul_f32 v[126:127], v[126:127], v[162:163] op_sel_hi:[1,0]
	v_pk_mul_f32 v[124:125], v[124:125], v[162:163] op_sel_hi:[1,0]
	v_pk_mul_f32 v[122:123], v[122:123], v[162:163] op_sel_hi:[1,0]
	v_pk_mul_f32 v[120:121], v[120:121], v[162:163] op_sel_hi:[1,0]
	v_pk_mul_f32 v[118:119], v[118:119], v[162:163] op_sel_hi:[1,0]
	v_pk_mul_f32 v[164:165], v[116:117], v[162:163] op_sel_hi:[1,0]
	v_pk_mul_f32 v[162:163], v[114:115], v[162:163] op_sel_hi:[1,0]
	v_cvt_pk_bf16_f32 v114, v126, v127
	v_cvt_pk_bf16_f32 v115, v128, v129
	v_cvt_pk_bf16_f32 v116, v122, v123
	v_cvt_pk_bf16_f32 v117, v124, v125
	v_lshl_add_u64 v[122:123], v[158:159], 0, v[138:139]
	v_cvt_pk_bf16_f32 v118, v118, v119
	v_cvt_pk_bf16_f32 v119, v120, v121
	v_cvt_pk_bf16_f32 v120, v162, v163
	v_cvt_pk_bf16_f32 v121, v164, v165
	global_store_dwordx4 v[122:123], v[114:117], off
	global_store_dwordx4 v[122:123], v[118:121], off offset:256
	s_nop 0
	v_lshlrev_b64 v[116:117], 11, v[156:157]
	v_lshl_add_u64 v[116:117], s[48:49], 0, v[116:117]
	v_or_b32_e32 v114, 32, v148
	v_lshl_add_u64 v[116:117], v[116:117], 0, s[10:11]
	v_ashrrev_i32_e32 v115, 31, v114
	v_lshl_add_u64 v[116:117], v[116:117], 0, v[138:139]
	v_fmamk_f32 v120, v232, 0x3a800000, v155
	v_rsq_f32_e32 v120, v120
	s_nop 0
	v_mul_f32_e32 v121, 0x3e38aa3b, v120
	v_cndmask_b32_e64 v120, v120, v121, s[6:7]
	v_pk_mul_f32 v[112:113], v[112:113], v[120:121] op_sel_hi:[1,0]
	v_pk_mul_f32 v[110:111], v[110:111], v[120:121] op_sel_hi:[1,0]
	v_pk_mul_f32 v[108:109], v[108:109], v[120:121] op_sel_hi:[1,0]
	v_pk_mul_f32 v[106:107], v[106:107], v[120:121] op_sel_hi:[1,0]
	v_pk_mul_f32 v[104:105], v[104:105], v[120:121] op_sel_hi:[1,0]
	v_pk_mul_f32 v[102:103], v[102:103], v[120:121] op_sel_hi:[1,0]
	v_pk_mul_f32 v[122:123], v[100:101], v[120:121] op_sel_hi:[1,0]
	v_pk_mul_f32 v[120:121], v[98:99], v[120:121] op_sel_hi:[1,0]
	v_cvt_pk_bf16_f32 v98, v110, v111
	v_cvt_pk_bf16_f32 v99, v112, v113
	v_cvt_pk_bf16_f32 v100, v106, v107
	v_cvt_pk_bf16_f32 v101, v108, v109
	v_cvt_pk_bf16_f32 v102, v102, v103
	v_cvt_pk_bf16_f32 v103, v104, v105
	v_cvt_pk_bf16_f32 v104, v120, v121
	v_cvt_pk_bf16_f32 v105, v122, v123
	global_store_dwordx4 v[116:117], v[98:101], off
	global_store_dwordx4 v[116:117], v[102:105], off offset:256
	s_nop 0
	v_lshlrev_b64 v[100:101], 11, v[114:115]
	v_lshl_add_u64 v[100:101], s[48:49], 0, v[100:101]
	v_or_b32_e32 v98, 48, v148
	v_lshl_add_u64 v[100:101], v[100:101], 0, s[10:11]
	v_ashrrev_i32_e32 v99, 31, v98
	v_lshl_add_u64 v[100:101], v[100:101], 0, v[138:139]
	v_fmamk_f32 v104, v233, 0x3a800000, v155
	v_rsq_f32_e32 v104, v104
	s_nop 0
	v_mul_f32_e32 v105, 0x3e38aa3b, v104
	v_cndmask_b32_e64 v104, v104, v105, s[6:7]
	v_pk_mul_f32 v[96:97], v[96:97], v[104:105] op_sel_hi:[1,0]
	v_pk_mul_f32 v[94:95], v[94:95], v[104:105] op_sel_hi:[1,0]
	v_pk_mul_f32 v[92:93], v[92:93], v[104:105] op_sel_hi:[1,0]
	v_pk_mul_f32 v[90:91], v[90:91], v[104:105] op_sel_hi:[1,0]
	v_pk_mul_f32 v[88:89], v[88:89], v[104:105] op_sel_hi:[1,0]
	v_pk_mul_f32 v[86:87], v[86:87], v[104:105] op_sel_hi:[1,0]
	v_pk_mul_f32 v[106:107], v[84:85], v[104:105] op_sel_hi:[1,0]
	v_pk_mul_f32 v[104:105], v[82:83], v[104:105] op_sel_hi:[1,0]
	v_cvt_pk_bf16_f32 v82, v94, v95
	v_cvt_pk_bf16_f32 v83, v96, v97
	v_cvt_pk_bf16_f32 v84, v90, v91
	v_cvt_pk_bf16_f32 v85, v92, v93
	v_cvt_pk_bf16_f32 v86, v86, v87
	v_cvt_pk_bf16_f32 v87, v88, v89
	v_cvt_pk_bf16_f32 v88, v104, v105
	v_cvt_pk_bf16_f32 v89, v106, v107
	global_store_dwordx4 v[100:101], v[82:85], off
	global_store_dwordx4 v[100:101], v[86:89], off offset:256
	s_nop 0
	v_lshlrev_b64 v[84:85], 11, v[98:99]
	v_lshl_add_u64 v[84:85], s[48:49], 0, v[84:85]
	v_add_u32_e32 v82, 0x80, v148
	v_lshl_add_u64 v[84:85], v[84:85], 0, s[10:11]
	v_ashrrev_i32_e32 v83, 31, v82
	v_lshl_add_u64 v[84:85], v[84:85], 0, v[138:139]
	v_fmamk_f32 v88, v234, 0x3a800000, v155
	v_rsq_f32_e32 v88, v88
	s_nop 0
	v_mul_f32_e32 v89, 0x3e38aa3b, v88
	v_cndmask_b32_e64 v88, v88, v89, s[6:7]
	v_pk_mul_f32 v[80:81], v[80:81], v[88:89] op_sel_hi:[1,0]
	v_pk_mul_f32 v[78:79], v[78:79], v[88:89] op_sel_hi:[1,0]
	v_pk_mul_f32 v[76:77], v[76:77], v[88:89] op_sel_hi:[1,0]
	v_pk_mul_f32 v[74:75], v[74:75], v[88:89] op_sel_hi:[1,0]
	v_pk_mul_f32 v[72:73], v[72:73], v[88:89] op_sel_hi:[1,0]
	v_pk_mul_f32 v[70:71], v[70:71], v[88:89] op_sel_hi:[1,0]
	v_pk_mul_f32 v[90:91], v[68:69], v[88:89] op_sel_hi:[1,0]
	v_pk_mul_f32 v[88:89], v[66:67], v[88:89] op_sel_hi:[1,0]
	v_cvt_pk_bf16_f32 v66, v78, v79
	v_cvt_pk_bf16_f32 v67, v80, v81
	v_cvt_pk_bf16_f32 v68, v74, v75
	v_cvt_pk_bf16_f32 v69, v76, v77
	v_cvt_pk_bf16_f32 v70, v70, v71
	v_cvt_pk_bf16_f32 v71, v72, v73
	v_cvt_pk_bf16_f32 v72, v88, v89
	v_cvt_pk_bf16_f32 v73, v90, v91
	global_store_dwordx4 v[84:85], v[66:69], off
	global_store_dwordx4 v[84:85], v[70:73], off offset:256
	s_nop 0
	v_lshlrev_b64 v[68:69], 11, v[82:83]
	v_lshl_add_u64 v[68:69], s[48:49], 0, v[68:69]
	v_add_u32_e32 v66, 0x90, v148
	v_lshl_add_u64 v[68:69], v[68:69], 0, s[10:11]
	v_ashrrev_i32_e32 v67, 31, v66
	v_lshl_add_u64 v[68:69], v[68:69], 0, v[138:139]
	v_fmamk_f32 v72, v235, 0x3a800000, v155
	v_rsq_f32_e32 v72, v72
	s_nop 0
	v_mul_f32_e32 v73, 0x3e38aa3b, v72
	v_cndmask_b32_e64 v72, v72, v73, s[6:7]
	v_pk_mul_f32 v[64:65], v[64:65], v[72:73] op_sel_hi:[1,0]
	v_pk_mul_f32 v[62:63], v[62:63], v[72:73] op_sel_hi:[1,0]
	v_pk_mul_f32 v[60:61], v[60:61], v[72:73] op_sel_hi:[1,0]
	v_pk_mul_f32 v[58:59], v[58:59], v[72:73] op_sel_hi:[1,0]
	v_pk_mul_f32 v[56:57], v[56:57], v[72:73] op_sel_hi:[1,0]
	v_pk_mul_f32 v[54:55], v[54:55], v[72:73] op_sel_hi:[1,0]
	v_pk_mul_f32 v[74:75], v[52:53], v[72:73] op_sel_hi:[1,0]
	v_pk_mul_f32 v[72:73], v[50:51], v[72:73] op_sel_hi:[1,0]
	v_cvt_pk_bf16_f32 v50, v62, v63
	v_cvt_pk_bf16_f32 v51, v64, v65
	v_cvt_pk_bf16_f32 v52, v58, v59
	v_cvt_pk_bf16_f32 v53, v60, v61
	v_cvt_pk_bf16_f32 v54, v54, v55
	v_cvt_pk_bf16_f32 v55, v56, v57
	v_cvt_pk_bf16_f32 v56, v72, v73
	v_cvt_pk_bf16_f32 v57, v74, v75
	global_store_dwordx4 v[68:69], v[50:53], off
	global_store_dwordx4 v[68:69], v[54:57], off offset:256
	s_nop 0
	v_lshlrev_b64 v[52:53], 11, v[66:67]
	v_lshl_add_u64 v[52:53], s[48:49], 0, v[52:53]
	v_add_u32_e32 v50, 0xa0, v148
	v_lshl_add_u64 v[52:53], v[52:53], 0, s[10:11]
	v_ashrrev_i32_e32 v51, 31, v50
	v_lshl_add_u64 v[52:53], v[52:53], 0, v[138:139]
	v_fmamk_f32 v56, v236, 0x3a800000, v155
	v_rsq_f32_e32 v56, v56
	s_nop 0
	v_mul_f32_e32 v57, 0x3e38aa3b, v56
	v_cndmask_b32_e64 v56, v56, v57, s[6:7]
	v_pk_mul_f32 v[48:49], v[48:49], v[56:57] op_sel_hi:[1,0]
	v_pk_mul_f32 v[46:47], v[46:47], v[56:57] op_sel_hi:[1,0]
	v_pk_mul_f32 v[44:45], v[44:45], v[56:57] op_sel_hi:[1,0]
	v_pk_mul_f32 v[42:43], v[42:43], v[56:57] op_sel_hi:[1,0]
	v_pk_mul_f32 v[40:41], v[40:41], v[56:57] op_sel_hi:[1,0]
	v_pk_mul_f32 v[38:39], v[38:39], v[56:57] op_sel_hi:[1,0]
	v_pk_mul_f32 v[58:59], v[36:37], v[56:57] op_sel_hi:[1,0]
	v_pk_mul_f32 v[56:57], v[34:35], v[56:57] op_sel_hi:[1,0]
	v_cvt_pk_bf16_f32 v34, v46, v47
	v_cvt_pk_bf16_f32 v35, v48, v49
	v_cvt_pk_bf16_f32 v36, v42, v43
	v_cvt_pk_bf16_f32 v37, v44, v45
	v_cvt_pk_bf16_f32 v38, v38, v39
	v_cvt_pk_bf16_f32 v39, v40, v41
	v_cvt_pk_bf16_f32 v40, v56, v57
	v_cvt_pk_bf16_f32 v41, v58, v59
	global_store_dwordx4 v[52:53], v[34:37], off
	global_store_dwordx4 v[52:53], v[38:41], off offset:256
	s_nop 0
	v_lshlrev_b64 v[36:37], 11, v[50:51]
	v_lshl_add_u64 v[36:37], s[48:49], 0, v[36:37]
	v_add_u32_e32 v34, 0xb0, v148
	v_lshl_add_u64 v[36:37], v[36:37], 0, s[10:11]
	v_ashrrev_i32_e32 v35, 31, v34
	v_lshl_add_u64 v[36:37], v[36:37], 0, v[138:139]
	v_fmamk_f32 v40, v237, 0x3a800000, v155
	v_rsq_f32_e32 v40, v40
	s_nop 0
	v_mul_f32_e32 v41, 0x3e38aa3b, v40
	v_cndmask_b32_e64 v40, v40, v41, s[6:7]
	v_pk_mul_f32 v[32:33], v[32:33], v[40:41] op_sel_hi:[1,0]
	v_pk_mul_f32 v[30:31], v[30:31], v[40:41] op_sel_hi:[1,0]
	v_pk_mul_f32 v[28:29], v[28:29], v[40:41] op_sel_hi:[1,0]
	v_pk_mul_f32 v[26:27], v[26:27], v[40:41] op_sel_hi:[1,0]
	v_pk_mul_f32 v[24:25], v[24:25], v[40:41] op_sel_hi:[1,0]
	v_pk_mul_f32 v[22:23], v[22:23], v[40:41] op_sel_hi:[1,0]
	v_pk_mul_f32 v[42:43], v[20:21], v[40:41] op_sel_hi:[1,0]
	v_pk_mul_f32 v[40:41], v[18:19], v[40:41] op_sel_hi:[1,0]
	v_cvt_pk_bf16_f32 v18, v30, v31
	v_cvt_pk_bf16_f32 v19, v32, v33
	v_cvt_pk_bf16_f32 v20, v26, v27
	v_cvt_pk_bf16_f32 v21, v28, v29
	v_cvt_pk_bf16_f32 v22, v22, v23
	v_cvt_pk_bf16_f32 v23, v24, v25
	v_cvt_pk_bf16_f32 v24, v40, v41
	v_cvt_pk_bf16_f32 v25, v42, v43
	global_store_dwordx4 v[36:37], v[18:21], off
	global_store_dwordx4 v[36:37], v[22:25], off offset:256
	s_nop 0
	v_lshlrev_b64 v[18:19], 11, v[34:35]
	v_lshl_add_u64 v[18:19], s[48:49], 0, v[18:19]
	v_lshl_add_u64 v[18:19], v[18:19], 0, s[10:11]
	v_lshl_add_u64 v[18:19], v[18:19], 0, v[138:139]
	v_fmamk_f32 v20, v238, 0x3a800000, v155
	v_rsq_f32_e32 v20, v20
	s_nop 0
	v_mul_f32_e32 v21, 0x3e38aa3b, v20
	v_cndmask_b32_e64 v20, v20, v21, s[6:7]
	v_pk_mul_f32 v[16:17], v[16:17], v[20:21] op_sel_hi:[1,0]
	v_pk_mul_f32 v[14:15], v[14:15], v[20:21] op_sel_hi:[1,0]
	v_pk_mul_f32 v[12:13], v[12:13], v[20:21] op_sel_hi:[1,0]
	v_pk_mul_f32 v[10:11], v[10:11], v[20:21] op_sel_hi:[1,0]
	v_pk_mul_f32 v[8:9], v[8:9], v[20:21] op_sel_hi:[1,0]
	v_pk_mul_f32 v[6:7], v[6:7], v[20:21] op_sel_hi:[1,0]
	v_pk_mul_f32 v[22:23], v[4:5], v[20:21] op_sel_hi:[1,0]
	v_pk_mul_f32 v[20:21], v[2:3], v[20:21] op_sel_hi:[1,0]
	v_cvt_pk_bf16_f32 v2, v14, v15
	v_cvt_pk_bf16_f32 v3, v16, v17
	v_cvt_pk_bf16_f32 v4, v10, v11
	v_cvt_pk_bf16_f32 v5, v12, v13
	v_cvt_pk_bf16_f32 v6, v6, v7
	v_cvt_pk_bf16_f32 v7, v8, v9
	v_cvt_pk_bf16_f32 v8, v20, v21
	v_cvt_pk_bf16_f32 v9, v22, v23
	global_store_dwordx4 v[18:19], v[2:5], off
	global_store_dwordx4 v[18:19], v[6:9], off offset:256
	s_cbranch_vccnz .LBB0_348
	s_andn2_b64 vcc, exec, s[12:13]
	s_cbranch_vccnz .LBB0_347
	s_barrier
	s_branch .LBB0_347

.LBB0_1360:
	v_lshl_add_u32 v148, s52, 8, v150
	v_ashrrev_i32_e32 v149, 31, v148
	v_lshl_add_u64 v[158:159], v[148:149], 2, s[12:13]
	global_load_dword v232, v[158:159], off offset:64
	global_load_dword v233, v[158:159], off offset:128
	global_load_dword v234, v[158:159], off offset:192
	global_load_dword v235, v[158:159], off offset:512
	global_load_dword v236, v[158:159], off offset:576
	global_load_dword v237, v[158:159], off offset:640
	global_load_dword v238, v[158:159], off offset:704
	global_load_dword v157, v[158:159], off
	v_and_b32_e32 v160, 64, v155
	v_xor_b32_e32 v162, 16, v155
	v_add_u32_e32 v164, 64, v160
	v_mov_b64_e32 v[158:159], s[14:15]
	v_cmp_lt_i32_e32 vcc, v162, v164
	v_mad_i64_i32 v[160:161], s[52:53], v148, s73, v[158:159]
	s_nop 0
	v_cndmask_b32_e32 v158, v155, v162, vcc
	v_xor_b32_e32 v163, 32, v155
	v_cmp_lt_i32_e32 vcc, v163, v164
	v_lshlrev_b32_e32 v158, 2, v158
	s_lshl_b32 s50, s50, 8
	s_ashr_i32 s51, s50, 31
	s_waitcnt vmcnt(0)
	v_fmamk_f32 v157, v157, 0x3a800000, v156
	v_rsq_f32_e32 v162, v157
	v_cndmask_b32_e32 v157, v155, v163, vcc
	v_lshlrev_b32_e32 v157, 2, v157
	v_pk_mul_f32 v[128:129], v[128:129], v[162:163] op_sel_hi:[1,0]
	v_pk_mul_f32 v[126:127], v[126:127], v[162:163] op_sel_hi:[1,0]
	v_pk_mul_f32 v[124:125], v[124:125], v[162:163] op_sel_hi:[1,0]
	v_pk_mul_f32 v[122:123], v[122:123], v[162:163] op_sel_hi:[1,0]
	v_pk_mul_f32 v[120:121], v[120:121], v[162:163] op_sel_hi:[1,0]
	v_pk_mul_f32 v[118:119], v[118:119], v[162:163] op_sel_hi:[1,0]
	v_pk_mul_f32 v[164:165], v[116:117], v[162:163] op_sel_hi:[1,0]
	v_pk_mul_f32 v[162:163], v[114:115], v[162:163] op_sel_hi:[1,0]
	v_mul_f32_e32 v159, v127, v127
	v_mul_f32_e32 v166, v129, v129
	v_mul_f32_e32 v167, v123, v123
	v_mul_f32_e32 v168, v125, v125
	v_cvt_pk_bf16_f32 v114, v126, v127
	v_cvt_pk_bf16_f32 v115, v128, v129
	v_cvt_pk_bf16_f32 v116, v122, v123
	v_cvt_pk_bf16_f32 v117, v124, v125
	v_mul_f32_e32 v123, v119, v119
	v_mul_f32_e32 v125, v121, v121
	v_mul_f32_e32 v127, v163, v163
	v_mul_f32_e32 v129, v165, v165
	v_fmac_f32_e32 v159, v126, v126
	v_fmac_f32_e32 v166, v128, v128
	v_fmac_f32_e32 v167, v122, v122
	v_fmac_f32_e32 v168, v124, v124
	v_fmac_f32_e32 v123, v118, v118
	v_fmac_f32_e32 v125, v120, v120
	v_fmac_f32_e32 v127, v162, v162
	v_fmac_f32_e32 v129, v164, v164
	v_add_f32_e32 v122, v159, v166
	v_add_f32_e32 v124, v167, v168
	v_add_f32_e32 v123, v123, v125
	v_add_f32_e32 v125, v127, v129
	v_add_f32_e32 v122, v122, v124
	v_add_f32_e32 v123, v123, v125
	v_add_f32_e32 v124, v122, v123
	ds_bpermute_b32 v125, v158, v124
	v_lshl_add_u64 v[122:123], s[50:51], 1, v[160:161]
	v_lshl_add_u64 v[122:123], v[122:123], 0, v[138:139]
	global_store_dwordx4 v[122:123], v[114:117], off
	s_waitcnt lgkmcnt(0)
	s_nop 0
	v_add_f32_e32 v114, v124, v125
	ds_bpermute_b32 v115, v157, v114
	v_cvt_pk_bf16_f32 v116, v118, v119
	v_cvt_pk_bf16_f32 v117, v120, v121
	v_cvt_pk_bf16_f32 v118, v162, v163
	v_cvt_pk_bf16_f32 v119, v164, v165
	global_store_dwordx4 v[122:123], v[116:119], off offset:256
	s_and_saveexec_b64 s[52:53], s[4:5]
	s_cbranch_execz .LBB0_1362
	v_lshl_add_u64 v[116:117], v[148:149], 2, s[16:17]
	s_waitcnt lgkmcnt(0)
	v_add_f32_e32 v114, v114, v115
	global_atomic_add_f32 v[116:117], v114, off
.LBB0_1362:
	s_or_b64 exec, exec, s[52:53]
	v_or_b32_e32 v114, 16, v148
	s_waitcnt lgkmcnt(0)
	v_ashrrev_i32_e32 v115, 31, v114
	v_mov_b64_e32 v[118:119], s[14:15]
	v_mad_i64_i32 v[118:119], s[52:53], v114, s73, v[118:119]
	v_fmamk_f32 v116, v232, 0x3a800000, v156
	v_rsq_f32_e32 v116, v116
	s_nop 0
	v_pk_mul_f32 v[112:113], v[112:113], v[116:117] op_sel_hi:[1,0]
	v_pk_mul_f32 v[110:111], v[110:111], v[116:117] op_sel_hi:[1,0]
	v_pk_mul_f32 v[108:109], v[108:109], v[116:117] op_sel_hi:[1,0]
	v_pk_mul_f32 v[106:107], v[106:107], v[116:117] op_sel_hi:[1,0]
	v_pk_mul_f32 v[104:105], v[104:105], v[116:117] op_sel_hi:[1,0]
	v_pk_mul_f32 v[102:103], v[102:103], v[116:117] op_sel_hi:[1,0]
	v_pk_mul_f32 v[120:121], v[100:101], v[116:117] op_sel_hi:[1,0]
	v_pk_mul_f32 v[116:117], v[98:99], v[116:117] op_sel_hi:[1,0]
	v_mul_f32_e32 v122, v111, v111
	v_mul_f32_e32 v123, v113, v113
	v_mul_f32_e32 v124, v107, v107
	v_mul_f32_e32 v125, v109, v109
	v_cvt_pk_bf16_f32 v98, v110, v111
	v_cvt_pk_bf16_f32 v99, v112, v113
	v_cvt_pk_bf16_f32 v100, v106, v107
	v_cvt_pk_bf16_f32 v101, v108, v109
	v_mul_f32_e32 v107, v103, v103
	v_mul_f32_e32 v109, v105, v105
	v_mul_f32_e32 v111, v117, v117
	v_mul_f32_e32 v113, v121, v121
	v_fmac_f32_e32 v122, v110, v110
	v_fmac_f32_e32 v123, v112, v112
	v_fmac_f32_e32 v124, v106, v106
	v_fmac_f32_e32 v125, v108, v108
	v_fmac_f32_e32 v107, v102, v102
	v_fmac_f32_e32 v109, v104, v104
	v_fmac_f32_e32 v111, v116, v116
	v_fmac_f32_e32 v113, v120, v120
	v_add_f32_e32 v106, v122, v123
	v_add_f32_e32 v108, v124, v125
	v_add_f32_e32 v107, v107, v109
	v_add_f32_e32 v109, v111, v113
	v_add_f32_e32 v106, v106, v108
	v_add_f32_e32 v107, v107, v109
	v_add_f32_e32 v108, v106, v107
	ds_bpermute_b32 v109, v158, v108
	v_lshl_add_u64 v[106:107], s[50:51], 1, v[118:119]
	v_lshl_add_u64 v[106:107], v[106:107], 0, v[138:139]
	global_store_dwordx4 v[106:107], v[98:101], off
	s_waitcnt lgkmcnt(0)
	s_nop 0
	v_add_f32_e32 v98, v108, v109
	ds_bpermute_b32 v99, v157, v98
	v_cvt_pk_bf16_f32 v100, v102, v103
	v_cvt_pk_bf16_f32 v101, v104, v105
	v_cvt_pk_bf16_f32 v102, v116, v117
	v_cvt_pk_bf16_f32 v103, v120, v121
	global_store_dwordx4 v[106:107], v[100:103], off offset:256
	s_and_saveexec_b64 s[52:53], s[4:5]
	s_cbranch_execz .LBB0_1364
	v_lshl_add_u64 v[100:101], v[114:115], 2, s[16:17]
	s_waitcnt lgkmcnt(0)
	v_add_f32_e32 v98, v98, v99
	global_atomic_add_f32 v[100:101], v98, off
.LBB0_1364:
	s_or_b64 exec, exec, s[52:53]
	v_or_b32_e32 v98, 32, v148
	s_waitcnt lgkmcnt(0)
	v_ashrrev_i32_e32 v99, 31, v98
	v_mov_b64_e32 v[102:103], s[14:15]
	v_mad_i64_i32 v[102:103], s[52:53], v98, s73, v[102:103]
	v_fmamk_f32 v100, v233, 0x3a800000, v156
	v_rsq_f32_e32 v100, v100
	s_nop 0
	v_pk_mul_f32 v[96:97], v[96:97], v[100:101] op_sel_hi:[1,0]
	v_pk_mul_f32 v[94:95], v[94:95], v[100:101] op_sel_hi:[1,0]
	v_pk_mul_f32 v[92:93], v[92:93], v[100:101] op_sel_hi:[1,0]
	v_pk_mul_f32 v[90:91], v[90:91], v[100:101] op_sel_hi:[1,0]
	v_pk_mul_f32 v[88:89], v[88:89], v[100:101] op_sel_hi:[1,0]
	v_pk_mul_f32 v[86:87], v[86:87], v[100:101] op_sel_hi:[1,0]
	v_pk_mul_f32 v[104:105], v[84:85], v[100:101] op_sel_hi:[1,0]
	v_pk_mul_f32 v[100:101], v[82:83], v[100:101] op_sel_hi:[1,0]
	v_mul_f32_e32 v106, v95, v95
	v_mul_f32_e32 v107, v97, v97
	v_mul_f32_e32 v108, v91, v91
	v_mul_f32_e32 v109, v93, v93
	v_cvt_pk_bf16_f32 v82, v94, v95
	v_cvt_pk_bf16_f32 v83, v96, v97
	v_cvt_pk_bf16_f32 v84, v90, v91
	v_cvt_pk_bf16_f32 v85, v92, v93
	v_mul_f32_e32 v91, v87, v87
	v_mul_f32_e32 v93, v89, v89
	v_mul_f32_e32 v95, v101, v101
	v_mul_f32_e32 v97, v105, v105
	v_fmac_f32_e32 v106, v94, v94
	v_fmac_f32_e32 v107, v96, v96
	v_fmac_f32_e32 v108, v90, v90
	v_fmac_f32_e32 v109, v92, v92
	v_fmac_f32_e32 v91, v86, v86
	v_fmac_f32_e32 v93, v88, v88
	v_fmac_f32_e32 v95, v100, v100
	v_fmac_f32_e32 v97, v104, v104
	v_add_f32_e32 v90, v106, v107
	v_add_f32_e32 v92, v108, v109
	v_add_f32_e32 v91, v91, v93
	v_add_f32_e32 v93, v95, v97
	v_add_f32_e32 v90, v90, v92
	v_add_f32_e32 v91, v91, v93
	v_add_f32_e32 v92, v90, v91
	ds_bpermute_b32 v93, v158, v92
	v_lshl_add_u64 v[90:91], s[50:51], 1, v[102:103]
	v_lshl_add_u64 v[90:91], v[90:91], 0, v[138:139]
	global_store_dwordx4 v[90:91], v[82:85], off
	s_waitcnt lgkmcnt(0)
	s_nop 0
	v_add_f32_e32 v82, v92, v93
	ds_bpermute_b32 v83, v157, v82
	v_cvt_pk_bf16_f32 v84, v86, v87
	v_cvt_pk_bf16_f32 v85, v88, v89
	v_cvt_pk_bf16_f32 v86, v100, v101
	v_cvt_pk_bf16_f32 v87, v104, v105
	global_store_dwordx4 v[90:91], v[84:87], off offset:256
	s_and_saveexec_b64 s[52:53], s[4:5]
	s_cbranch_execz .LBB0_1366
	v_lshl_add_u64 v[84:85], v[98:99], 2, s[16:17]
	s_waitcnt lgkmcnt(0)
	v_add_f32_e32 v82, v82, v83
	global_atomic_add_f32 v[84:85], v82, off
.LBB0_1366:
	s_or_b64 exec, exec, s[52:53]
	v_or_b32_e32 v82, 48, v148
	s_waitcnt lgkmcnt(0)
	v_ashrrev_i32_e32 v83, 31, v82
	v_mov_b64_e32 v[86:87], s[14:15]
	v_mad_i64_i32 v[86:87], s[52:53], v82, s73, v[86:87]
	v_fmamk_f32 v84, v234, 0x3a800000, v156
	v_rsq_f32_e32 v84, v84
	s_nop 0
	v_pk_mul_f32 v[80:81], v[80:81], v[84:85] op_sel_hi:[1,0]
	v_pk_mul_f32 v[78:79], v[78:79], v[84:85] op_sel_hi:[1,0]
	v_pk_mul_f32 v[76:77], v[76:77], v[84:85] op_sel_hi:[1,0]
	v_pk_mul_f32 v[74:75], v[74:75], v[84:85] op_sel_hi:[1,0]
	v_pk_mul_f32 v[72:73], v[72:73], v[84:85] op_sel_hi:[1,0]
	v_pk_mul_f32 v[70:71], v[70:71], v[84:85] op_sel_hi:[1,0]
	v_pk_mul_f32 v[88:89], v[68:69], v[84:85] op_sel_hi:[1,0]
	v_pk_mul_f32 v[84:85], v[66:67], v[84:85] op_sel_hi:[1,0]
	v_mul_f32_e32 v90, v79, v79
	v_mul_f32_e32 v91, v81, v81
	v_mul_f32_e32 v92, v75, v75
	v_mul_f32_e32 v93, v77, v77
	v_cvt_pk_bf16_f32 v66, v78, v79
	v_cvt_pk_bf16_f32 v67, v80, v81
	v_cvt_pk_bf16_f32 v68, v74, v75
	v_cvt_pk_bf16_f32 v69, v76, v77
	v_mul_f32_e32 v75, v71, v71
	v_mul_f32_e32 v77, v73, v73
	v_mul_f32_e32 v79, v85, v85
	v_mul_f32_e32 v81, v89, v89
	v_fmac_f32_e32 v90, v78, v78
	v_fmac_f32_e32 v91, v80, v80
	v_fmac_f32_e32 v92, v74, v74
	v_fmac_f32_e32 v93, v76, v76
	v_fmac_f32_e32 v75, v70, v70
	v_fmac_f32_e32 v77, v72, v72
	v_fmac_f32_e32 v79, v84, v84
	v_fmac_f32_e32 v81, v88, v88
	v_add_f32_e32 v74, v90, v91
	v_add_f32_e32 v76, v92, v93
	v_add_f32_e32 v75, v75, v77
	v_add_f32_e32 v77, v79, v81
	v_add_f32_e32 v74, v74, v76
	v_add_f32_e32 v75, v75, v77
	v_add_f32_e32 v76, v74, v75
	ds_bpermute_b32 v77, v158, v76
	v_lshl_add_u64 v[74:75], s[50:51], 1, v[86:87]
	v_lshl_add_u64 v[74:75], v[74:75], 0, v[138:139]
	global_store_dwordx4 v[74:75], v[66:69], off
	s_waitcnt lgkmcnt(0)
	s_nop 0
	v_add_f32_e32 v66, v76, v77
	ds_bpermute_b32 v67, v157, v66
	v_cvt_pk_bf16_f32 v68, v70, v71
	v_cvt_pk_bf16_f32 v69, v72, v73
	v_cvt_pk_bf16_f32 v70, v84, v85
	v_cvt_pk_bf16_f32 v71, v88, v89
	global_store_dwordx4 v[74:75], v[68:71], off offset:256
	s_and_saveexec_b64 s[52:53], s[4:5]
	s_cbranch_execz .LBB0_1368
	v_lshl_add_u64 v[68:69], v[82:83], 2, s[16:17]
	s_waitcnt lgkmcnt(0)
	v_add_f32_e32 v66, v66, v67
	global_atomic_add_f32 v[68:69], v66, off
.LBB0_1368:
	s_or_b64 exec, exec, s[52:53]
	v_add_u32_e32 v66, 0x80, v148
	s_waitcnt lgkmcnt(0)
	v_ashrrev_i32_e32 v67, 31, v66
	v_mov_b64_e32 v[70:71], s[14:15]
	v_mad_i64_i32 v[70:71], s[52:53], v66, s73, v[70:71]
	v_fmamk_f32 v68, v235, 0x3a800000, v156
	v_rsq_f32_e32 v68, v68
	s_nop 0
	v_pk_mul_f32 v[64:65], v[64:65], v[68:69] op_sel_hi:[1,0]
	v_pk_mul_f32 v[62:63], v[62:63], v[68:69] op_sel_hi:[1,0]
	v_pk_mul_f32 v[60:61], v[60:61], v[68:69] op_sel_hi:[1,0]
	v_pk_mul_f32 v[58:59], v[58:59], v[68:69] op_sel_hi:[1,0]
	v_pk_mul_f32 v[56:57], v[56:57], v[68:69] op_sel_hi:[1,0]
	v_pk_mul_f32 v[54:55], v[54:55], v[68:69] op_sel_hi:[1,0]
	v_pk_mul_f32 v[72:73], v[52:53], v[68:69] op_sel_hi:[1,0]
	v_pk_mul_f32 v[68:69], v[50:51], v[68:69] op_sel_hi:[1,0]
	v_mul_f32_e32 v74, v63, v63
	v_mul_f32_e32 v75, v65, v65
	v_mul_f32_e32 v76, v59, v59
	v_mul_f32_e32 v77, v61, v61
	v_cvt_pk_bf16_f32 v50, v62, v63
	v_cvt_pk_bf16_f32 v51, v64, v65
	v_cvt_pk_bf16_f32 v52, v58, v59
	v_cvt_pk_bf16_f32 v53, v60, v61
	v_mul_f32_e32 v59, v55, v55
	v_mul_f32_e32 v61, v57, v57
	v_mul_f32_e32 v63, v69, v69
	v_mul_f32_e32 v65, v73, v73
	v_fmac_f32_e32 v74, v62, v62
	v_fmac_f32_e32 v75, v64, v64
	v_fmac_f32_e32 v76, v58, v58
	v_fmac_f32_e32 v77, v60, v60
	v_fmac_f32_e32 v59, v54, v54
	v_fmac_f32_e32 v61, v56, v56
	v_fmac_f32_e32 v63, v68, v68
	v_fmac_f32_e32 v65, v72, v72
	v_add_f32_e32 v58, v74, v75
	v_add_f32_e32 v60, v76, v77
	v_add_f32_e32 v59, v59, v61
	v_add_f32_e32 v61, v63, v65
	v_add_f32_e32 v58, v58, v60
	v_add_f32_e32 v59, v59, v61
	v_add_f32_e32 v60, v58, v59
	ds_bpermute_b32 v61, v158, v60
	v_lshl_add_u64 v[58:59], s[50:51], 1, v[70:71]
	v_lshl_add_u64 v[58:59], v[58:59], 0, v[138:139]
	global_store_dwordx4 v[58:59], v[50:53], off
	s_waitcnt lgkmcnt(0)
	s_nop 0
	v_add_f32_e32 v50, v60, v61
	ds_bpermute_b32 v51, v157, v50
	v_cvt_pk_bf16_f32 v52, v54, v55
	v_cvt_pk_bf16_f32 v53, v56, v57
	v_cvt_pk_bf16_f32 v54, v68, v69
	v_cvt_pk_bf16_f32 v55, v72, v73
	global_store_dwordx4 v[58:59], v[52:55], off offset:256
	s_and_saveexec_b64 s[52:53], s[4:5]
	s_cbranch_execz .LBB0_1370
	v_lshl_add_u64 v[52:53], v[66:67], 2, s[16:17]
	s_waitcnt lgkmcnt(0)
	v_add_f32_e32 v50, v50, v51
	global_atomic_add_f32 v[52:53], v50, off
.LBB0_1370:
	s_or_b64 exec, exec, s[52:53]
	v_add_u32_e32 v50, 0x90, v148
	s_waitcnt lgkmcnt(0)
	v_ashrrev_i32_e32 v51, 31, v50
	v_mov_b64_e32 v[54:55], s[14:15]
	v_mad_i64_i32 v[54:55], s[52:53], v50, s73, v[54:55]
	v_fmamk_f32 v52, v236, 0x3a800000, v156
	v_rsq_f32_e32 v52, v52
	s_nop 0
	v_pk_mul_f32 v[48:49], v[48:49], v[52:53] op_sel_hi:[1,0]
	v_pk_mul_f32 v[46:47], v[46:47], v[52:53] op_sel_hi:[1,0]
	v_pk_mul_f32 v[44:45], v[44:45], v[52:53] op_sel_hi:[1,0]
	v_pk_mul_f32 v[42:43], v[42:43], v[52:53] op_sel_hi:[1,0]
	v_pk_mul_f32 v[40:41], v[40:41], v[52:53] op_sel_hi:[1,0]
	v_pk_mul_f32 v[38:39], v[38:39], v[52:53] op_sel_hi:[1,0]
	v_pk_mul_f32 v[56:57], v[36:37], v[52:53] op_sel_hi:[1,0]
	v_pk_mul_f32 v[52:53], v[34:35], v[52:53] op_sel_hi:[1,0]
	v_mul_f32_e32 v58, v47, v47
	v_mul_f32_e32 v59, v49, v49
	v_mul_f32_e32 v60, v43, v43
	v_mul_f32_e32 v61, v45, v45
	v_cvt_pk_bf16_f32 v34, v46, v47
	v_cvt_pk_bf16_f32 v35, v48, v49
	v_cvt_pk_bf16_f32 v36, v42, v43
	v_cvt_pk_bf16_f32 v37, v44, v45
	v_mul_f32_e32 v43, v39, v39
	v_mul_f32_e32 v45, v41, v41
	v_mul_f32_e32 v47, v53, v53
	v_mul_f32_e32 v49, v57, v57
	v_fmac_f32_e32 v58, v46, v46
	v_fmac_f32_e32 v59, v48, v48
	v_fmac_f32_e32 v60, v42, v42
	v_fmac_f32_e32 v61, v44, v44
	v_fmac_f32_e32 v43, v38, v38
	v_fmac_f32_e32 v45, v40, v40
	v_fmac_f32_e32 v47, v52, v52
	v_fmac_f32_e32 v49, v56, v56
	v_add_f32_e32 v42, v58, v59
	v_add_f32_e32 v44, v60, v61
	v_add_f32_e32 v43, v43, v45
	v_add_f32_e32 v45, v47, v49
	v_add_f32_e32 v42, v42, v44
	v_add_f32_e32 v43, v43, v45
	v_add_f32_e32 v44, v42, v43
	ds_bpermute_b32 v45, v158, v44
	v_lshl_add_u64 v[42:43], s[50:51], 1, v[54:55]
	v_lshl_add_u64 v[42:43], v[42:43], 0, v[138:139]
	global_store_dwordx4 v[42:43], v[34:37], off
	s_waitcnt lgkmcnt(0)
	s_nop 0
	v_add_f32_e32 v34, v44, v45
	ds_bpermute_b32 v35, v157, v34
	v_cvt_pk_bf16_f32 v36, v38, v39
	v_cvt_pk_bf16_f32 v37, v40, v41
	v_cvt_pk_bf16_f32 v38, v52, v53
	v_cvt_pk_bf16_f32 v39, v56, v57
	global_store_dwordx4 v[42:43], v[36:39], off offset:256
	s_and_saveexec_b64 s[52:53], s[4:5]
	s_cbranch_execz .LBB0_1372
	v_lshl_add_u64 v[36:37], v[50:51], 2, s[16:17]
	s_waitcnt lgkmcnt(0)
	v_add_f32_e32 v34, v34, v35
	global_atomic_add_f32 v[36:37], v34, off
.LBB0_1372:
	s_or_b64 exec, exec, s[52:53]
	v_add_u32_e32 v34, 0xa0, v148
	s_waitcnt lgkmcnt(0)
	v_ashrrev_i32_e32 v35, 31, v34
	v_mov_b64_e32 v[38:39], s[14:15]
	v_mad_i64_i32 v[38:39], s[52:53], v34, s73, v[38:39]
	v_fmamk_f32 v36, v237, 0x3a800000, v156
	v_rsq_f32_e32 v36, v36
	s_nop 0
	v_pk_mul_f32 v[32:33], v[32:33], v[36:37] op_sel_hi:[1,0]
	v_pk_mul_f32 v[30:31], v[30:31], v[36:37] op_sel_hi:[1,0]
	v_pk_mul_f32 v[28:29], v[28:29], v[36:37] op_sel_hi:[1,0]
	v_pk_mul_f32 v[26:27], v[26:27], v[36:37] op_sel_hi:[1,0]
	v_pk_mul_f32 v[24:25], v[24:25], v[36:37] op_sel_hi:[1,0]
	v_pk_mul_f32 v[22:23], v[22:23], v[36:37] op_sel_hi:[1,0]
	v_pk_mul_f32 v[40:41], v[20:21], v[36:37] op_sel_hi:[1,0]
	v_pk_mul_f32 v[36:37], v[18:19], v[36:37] op_sel_hi:[1,0]
	v_mul_f32_e32 v42, v31, v31
	v_mul_f32_e32 v43, v33, v33
	v_mul_f32_e32 v44, v27, v27
	v_mul_f32_e32 v45, v29, v29
	v_cvt_pk_bf16_f32 v18, v30, v31
	v_cvt_pk_bf16_f32 v19, v32, v33
	v_cvt_pk_bf16_f32 v20, v26, v27
	v_cvt_pk_bf16_f32 v21, v28, v29
	v_mul_f32_e32 v27, v23, v23
	v_mul_f32_e32 v29, v25, v25
	v_mul_f32_e32 v31, v37, v37
	v_mul_f32_e32 v33, v41, v41
	v_fmac_f32_e32 v42, v30, v30
	v_fmac_f32_e32 v43, v32, v32
	v_fmac_f32_e32 v44, v26, v26
	v_fmac_f32_e32 v45, v28, v28
	v_fmac_f32_e32 v27, v22, v22
	v_fmac_f32_e32 v29, v24, v24
	v_fmac_f32_e32 v31, v36, v36
	v_fmac_f32_e32 v33, v40, v40
	v_add_f32_e32 v26, v42, v43
	v_add_f32_e32 v28, v44, v45
	v_add_f32_e32 v27, v27, v29
	v_add_f32_e32 v29, v31, v33
	v_add_f32_e32 v26, v26, v28
	v_add_f32_e32 v27, v27, v29
	v_add_f32_e32 v28, v26, v27
	ds_bpermute_b32 v29, v158, v28
	v_lshl_add_u64 v[26:27], s[50:51], 1, v[38:39]
	v_lshl_add_u64 v[26:27], v[26:27], 0, v[138:139]
	global_store_dwordx4 v[26:27], v[18:21], off
	s_waitcnt lgkmcnt(0)
	s_nop 0
	v_add_f32_e32 v18, v28, v29
	ds_bpermute_b32 v19, v157, v18
	v_cvt_pk_bf16_f32 v20, v22, v23
	v_cvt_pk_bf16_f32 v21, v24, v25
	v_cvt_pk_bf16_f32 v22, v36, v37
	v_cvt_pk_bf16_f32 v23, v40, v41
	global_store_dwordx4 v[26:27], v[20:23], off offset:256
	s_and_saveexec_b64 s[52:53], s[4:5]
	s_cbranch_execz .LBB0_1374
	v_lshl_add_u64 v[20:21], v[34:35], 2, s[16:17]
	s_waitcnt lgkmcnt(0)
	v_add_f32_e32 v18, v18, v19
	global_atomic_add_f32 v[20:21], v18, off
.LBB0_1374:
	s_or_b64 exec, exec, s[52:53]
	v_add_u32_e32 v18, 0xb0, v148
	s_waitcnt lgkmcnt(0)
	v_ashrrev_i32_e32 v19, 31, v18
	v_mov_b64_e32 v[22:23], s[14:15]
	v_mad_i64_i32 v[22:23], s[52:53], v18, s73, v[22:23]
	v_fmamk_f32 v20, v238, 0x3a800000, v156
	v_rsq_f32_e32 v20, v20
	s_nop 0
	v_pk_mul_f32 v[16:17], v[16:17], v[20:21] op_sel_hi:[1,0]
	v_pk_mul_f32 v[14:15], v[14:15], v[20:21] op_sel_hi:[1,0]
	v_pk_mul_f32 v[12:13], v[12:13], v[20:21] op_sel_hi:[1,0]
	v_pk_mul_f32 v[10:11], v[10:11], v[20:21] op_sel_hi:[1,0]
	v_pk_mul_f32 v[8:9], v[8:9], v[20:21] op_sel_hi:[1,0]
	v_pk_mul_f32 v[6:7], v[6:7], v[20:21] op_sel_hi:[1,0]
	v_pk_mul_f32 v[24:25], v[4:5], v[20:21] op_sel_hi:[1,0]
	v_pk_mul_f32 v[20:21], v[2:3], v[20:21] op_sel_hi:[1,0]
	v_mul_f32_e32 v26, v15, v15
	v_mul_f32_e32 v27, v17, v17
	v_mul_f32_e32 v28, v11, v11
	v_mul_f32_e32 v29, v13, v13
	v_cvt_pk_bf16_f32 v2, v14, v15
	v_cvt_pk_bf16_f32 v3, v16, v17
	v_cvt_pk_bf16_f32 v4, v10, v11
	v_cvt_pk_bf16_f32 v5, v12, v13
	v_mul_f32_e32 v11, v7, v7
	v_mul_f32_e32 v13, v9, v9
	v_mul_f32_e32 v15, v21, v21
	v_mul_f32_e32 v17, v25, v25
	v_fmac_f32_e32 v26, v14, v14
	v_fmac_f32_e32 v27, v16, v16
	v_fmac_f32_e32 v28, v10, v10
	v_fmac_f32_e32 v29, v12, v12
	v_fmac_f32_e32 v11, v6, v6
	v_fmac_f32_e32 v13, v8, v8
	v_fmac_f32_e32 v15, v20, v20
	v_fmac_f32_e32 v17, v24, v24
	v_add_f32_e32 v10, v26, v27
	v_add_f32_e32 v12, v28, v29
	v_add_f32_e32 v11, v11, v13
	v_add_f32_e32 v13, v15, v17
	v_add_f32_e32 v10, v10, v12
	v_add_f32_e32 v11, v11, v13
	v_add_f32_e32 v12, v10, v11
	ds_bpermute_b32 v13, v158, v12
	v_lshl_add_u64 v[10:11], s[50:51], 1, v[22:23]
	v_lshl_add_u64 v[10:11], v[10:11], 0, v[138:139]
	global_store_dwordx4 v[10:11], v[2:5], off
	s_waitcnt lgkmcnt(0)
	s_nop 0
	v_add_f32_e32 v2, v12, v13
	ds_bpermute_b32 v3, v157, v2
	v_cvt_pk_bf16_f32 v4, v6, v7
	v_cvt_pk_bf16_f32 v5, v8, v9
	v_cvt_pk_bf16_f32 v6, v20, v21
	v_cvt_pk_bf16_f32 v7, v24, v25
	global_store_dwordx4 v[10:11], v[4:7], off offset:256
	s_and_saveexec_b64 s[50:51], s[4:5]
	s_cbranch_execz .LBB0_1376
	v_lshl_add_u64 v[4:5], v[18:19], 2, s[16:17]
	s_waitcnt lgkmcnt(0)
	v_add_f32_e32 v2, v2, v3
	global_atomic_add_f32 v[4:5], v2, off

.LBB0_1398:
	s_lshl_b32 s45, s54, 8
	v_add_u32_e32 v140, s45, v142
	v_ashrrev_i32_e32 v141, 31, v140
	v_lshl_add_u64 v[152:153], v[140:141], 2, s[10:11]
	global_load_dword v232, v[152:153], off offset:64
	global_load_dword v233, v[152:153], off offset:128
	global_load_dword v234, v[152:153], off offset:192
	global_load_dword v235, v[152:153], off offset:512
	global_load_dword v236, v[152:153], off offset:576
	global_load_dword v237, v[152:153], off offset:640
	global_load_dword v238, v[152:153], off offset:704
	global_load_dword v160, v[152:153], off
	v_lshlrev_b64 v[154:155], 11, v[140:141]
	s_lshl_b32 s54, s83, 7
	s_ashr_i32 s55, s54, 31
	s_lshl_b64 s[54:55], s[54:55], 1
	v_lshl_add_u64 v[158:159], s[12:13], 0, v[154:155]
	v_add_u32_e32 v152, s45, v143
	v_lshl_add_u64 v[154:155], s[14:15], 0, v[154:155]
	v_lshl_add_u64 v[158:159], v[158:159], 0, s[54:55]
	v_ashrrev_i32_e32 v153, 31, v152
	v_lshl_add_u64 v[154:155], v[154:155], 0, s[54:55]
	v_lshl_add_u64 v[158:159], v[158:159], 0, v[138:139]
	v_lshl_add_u64 v[154:155], v[154:155], 0, v[138:139]
	s_andn2_b64 vcc, exec, s[52:53]
	s_mov_b64 s[52:53], -1
	s_waitcnt vmcnt(0)
	v_fmamk_f32 v141, v160, 0x3b800000, v149
	v_rsq_f32_e32 v160, v141
	s_nop 0
	v_pk_mul_f32 v[116:117], v[116:117], v[160:161] op_sel_hi:[1,0]
	v_pk_mul_f32 v[114:115], v[114:115], v[160:161] op_sel_hi:[1,0]
	v_pk_mul_f32 v[120:121], v[120:121], v[160:161] op_sel_hi:[1,0]
	v_pk_mul_f32 v[118:119], v[118:119], v[160:161] op_sel_hi:[1,0]
	v_pk_mul_f32 v[124:125], v[124:125], v[160:161] op_sel_hi:[1,0]
	v_pk_mul_f32 v[122:123], v[122:123], v[160:161] op_sel_hi:[1,0]
	v_pk_mul_f32 v[128:129], v[128:129], v[160:161] op_sel_hi:[1,0]
	v_pk_mul_f32 v[126:127], v[126:127], v[160:161] op_sel_hi:[1,0]
	v_cvt_pk_bf16_f32 v114, v114, v115
	v_cvt_pk_bf16_f32 v115, v116, v117
	v_cvt_pk_bf16_f32 v116, v118, v119
	v_cvt_pk_bf16_f32 v117, v120, v121
	v_cvt_pk_bf16_f32 v118, v122, v123
	v_cvt_pk_bf16_f32 v119, v124, v125
	v_cvt_pk_bf16_f32 v120, v126, v127
	v_cvt_pk_bf16_f32 v121, v128, v129
	global_store_dwordx4 v[158:159], v[114:117], off
	global_store_dwordx4 v[154:155], v[118:121], off
	s_nop 0
	v_lshlrev_b64 v[116:117], 11, v[152:153]
	v_lshl_add_u64 v[120:121], s[12:13], 0, v[116:117]
	v_add_u32_e32 v114, s45, v144
	v_lshl_add_u64 v[116:117], s[14:15], 0, v[116:117]
	v_lshl_add_u64 v[120:121], v[120:121], 0, s[54:55]
	v_ashrrev_i32_e32 v115, 31, v114
	v_lshl_add_u64 v[116:117], v[116:117], 0, s[54:55]
	v_lshl_add_u64 v[120:121], v[120:121], 0, v[138:139]
	v_lshl_add_u64 v[116:117], v[116:117], 0, v[138:139]
	v_fmamk_f32 v122, v232, 0x3b800000, v149
	v_rsq_f32_e32 v122, v122
	s_nop 0
	v_pk_mul_f32 v[100:101], v[100:101], v[122:123] op_sel_hi:[1,0]
	v_pk_mul_f32 v[98:99], v[98:99], v[122:123] op_sel_hi:[1,0]
	v_pk_mul_f32 v[104:105], v[104:105], v[122:123] op_sel_hi:[1,0]
	v_pk_mul_f32 v[102:103], v[102:103], v[122:123] op_sel_hi:[1,0]
	v_pk_mul_f32 v[108:109], v[108:109], v[122:123] op_sel_hi:[1,0]
	v_pk_mul_f32 v[106:107], v[106:107], v[122:123] op_sel_hi:[1,0]
	v_pk_mul_f32 v[112:113], v[112:113], v[122:123] op_sel_hi:[1,0]
	v_pk_mul_f32 v[110:111], v[110:111], v[122:123] op_sel_hi:[1,0]
	v_cvt_pk_bf16_f32 v98, v98, v99
	v_cvt_pk_bf16_f32 v99, v100, v101
	v_cvt_pk_bf16_f32 v100, v102, v103
	v_cvt_pk_bf16_f32 v101, v104, v105
	v_cvt_pk_bf16_f32 v102, v106, v107
	v_cvt_pk_bf16_f32 v103, v108, v109
	v_cvt_pk_bf16_f32 v104, v110, v111
	v_cvt_pk_bf16_f32 v105, v112, v113
	global_store_dwordx4 v[120:121], v[98:101], off
	global_store_dwordx4 v[116:117], v[102:105], off
	s_nop 0
	v_lshlrev_b64 v[100:101], 11, v[114:115]
	v_lshl_add_u64 v[104:105], s[12:13], 0, v[100:101]
	v_add_u32_e32 v98, s45, v145
	v_lshl_add_u64 v[100:101], s[14:15], 0, v[100:101]
	v_lshl_add_u64 v[104:105], v[104:105], 0, s[54:55]
	v_ashrrev_i32_e32 v99, 31, v98
	v_lshl_add_u64 v[100:101], v[100:101], 0, s[54:55]
	v_lshl_add_u64 v[104:105], v[104:105], 0, v[138:139]
	v_lshl_add_u64 v[100:101], v[100:101], 0, v[138:139]
	v_fmamk_f32 v106, v233, 0x3b800000, v149
	v_rsq_f32_e32 v106, v106
	s_nop 0
	v_pk_mul_f32 v[84:85], v[84:85], v[106:107] op_sel_hi:[1,0]
	v_pk_mul_f32 v[82:83], v[82:83], v[106:107] op_sel_hi:[1,0]
	v_pk_mul_f32 v[88:89], v[88:89], v[106:107] op_sel_hi:[1,0]
	v_pk_mul_f32 v[86:87], v[86:87], v[106:107] op_sel_hi:[1,0]
	v_pk_mul_f32 v[92:93], v[92:93], v[106:107] op_sel_hi:[1,0]
	v_pk_mul_f32 v[90:91], v[90:91], v[106:107] op_sel_hi:[1,0]
	v_pk_mul_f32 v[96:97], v[96:97], v[106:107] op_sel_hi:[1,0]
	v_pk_mul_f32 v[94:95], v[94:95], v[106:107] op_sel_hi:[1,0]
	v_cvt_pk_bf16_f32 v82, v82, v83
	v_cvt_pk_bf16_f32 v83, v84, v85
	v_cvt_pk_bf16_f32 v84, v86, v87
	v_cvt_pk_bf16_f32 v85, v88, v89
	v_cvt_pk_bf16_f32 v86, v90, v91
	v_cvt_pk_bf16_f32 v87, v92, v93
	v_cvt_pk_bf16_f32 v88, v94, v95
	v_cvt_pk_bf16_f32 v89, v96, v97
	global_store_dwordx4 v[104:105], v[82:85], off
	global_store_dwordx4 v[100:101], v[86:89], off
	s_nop 0
	v_lshlrev_b64 v[84:85], 11, v[98:99]
	v_lshl_add_u64 v[86:87], s[12:13], 0, v[84:85]
	v_add_u32_e32 v82, 0x80, v140
	v_lshl_add_u64 v[84:85], s[14:15], 0, v[84:85]
	v_lshl_add_u64 v[86:87], v[86:87], 0, s[54:55]
	v_ashrrev_i32_e32 v83, 31, v82
	v_lshl_add_u64 v[84:85], v[84:85], 0, s[54:55]
	v_lshl_add_u64 v[86:87], v[86:87], 0, v[138:139]
	v_lshl_add_u64 v[84:85], v[84:85], 0, v[138:139]
	v_fmamk_f32 v90, v234, 0x3b800000, v149
	v_rsq_f32_e32 v90, v90
	s_nop 0
	v_pk_mul_f32 v[68:69], v[68:69], v[90:91] op_sel_hi:[1,0]
	v_pk_mul_f32 v[66:67], v[66:67], v[90:91] op_sel_hi:[1,0]
	v_pk_mul_f32 v[72:73], v[72:73], v[90:91] op_sel_hi:[1,0]
	v_pk_mul_f32 v[70:71], v[70:71], v[90:91] op_sel_hi:[1,0]
	v_pk_mul_f32 v[76:77], v[76:77], v[90:91] op_sel_hi:[1,0]
	v_pk_mul_f32 v[74:75], v[74:75], v[90:91] op_sel_hi:[1,0]
	v_pk_mul_f32 v[80:81], v[80:81], v[90:91] op_sel_hi:[1,0]
	v_pk_mul_f32 v[78:79], v[78:79], v[90:91] op_sel_hi:[1,0]
	v_cvt_pk_bf16_f32 v66, v66, v67
	v_cvt_pk_bf16_f32 v67, v68, v69
	v_cvt_pk_bf16_f32 v68, v70, v71
	v_cvt_pk_bf16_f32 v69, v72, v73
	v_cvt_pk_bf16_f32 v70, v74, v75
	v_cvt_pk_bf16_f32 v71, v76, v77
	v_cvt_pk_bf16_f32 v72, v78, v79
	v_cvt_pk_bf16_f32 v73, v80, v81
	global_store_dwordx4 v[86:87], v[66:69], off
	global_store_dwordx4 v[84:85], v[70:73], off
	s_nop 0
	v_lshlrev_b64 v[68:69], 11, v[82:83]
	v_lshl_add_u64 v[72:73], s[12:13], 0, v[68:69]
	v_add_u32_e32 v66, 0x90, v140
	v_lshl_add_u64 v[68:69], s[14:15], 0, v[68:69]
	v_lshl_add_u64 v[72:73], v[72:73], 0, s[54:55]
	v_ashrrev_i32_e32 v67, 31, v66
	v_lshl_add_u64 v[68:69], v[68:69], 0, s[54:55]
	v_lshl_add_u64 v[72:73], v[72:73], 0, v[138:139]
	v_lshl_add_u64 v[68:69], v[68:69], 0, v[138:139]
	v_fmamk_f32 v74, v235, 0x3b800000, v149
	v_rsq_f32_e32 v74, v74
	s_nop 0
	v_pk_mul_f32 v[52:53], v[52:53], v[74:75] op_sel_hi:[1,0]
	v_pk_mul_f32 v[50:51], v[50:51], v[74:75] op_sel_hi:[1,0]
	v_pk_mul_f32 v[56:57], v[56:57], v[74:75] op_sel_hi:[1,0]
	v_pk_mul_f32 v[54:55], v[54:55], v[74:75] op_sel_hi:[1,0]
	v_pk_mul_f32 v[60:61], v[60:61], v[74:75] op_sel_hi:[1,0]
	v_pk_mul_f32 v[58:59], v[58:59], v[74:75] op_sel_hi:[1,0]
	v_pk_mul_f32 v[64:65], v[64:65], v[74:75] op_sel_hi:[1,0]
	v_pk_mul_f32 v[62:63], v[62:63], v[74:75] op_sel_hi:[1,0]
	v_cvt_pk_bf16_f32 v50, v50, v51
	v_cvt_pk_bf16_f32 v51, v52, v53
	v_cvt_pk_bf16_f32 v52, v54, v55
	v_cvt_pk_bf16_f32 v53, v56, v57
	v_cvt_pk_bf16_f32 v54, v58, v59
	v_cvt_pk_bf16_f32 v55, v60, v61
	v_cvt_pk_bf16_f32 v56, v62, v63
	v_cvt_pk_bf16_f32 v57, v64, v65
	global_store_dwordx4 v[72:73], v[50:53], off
	global_store_dwordx4 v[68:69], v[54:57], off
	s_nop 0
	v_lshlrev_b64 v[52:53], 11, v[66:67]
	v_lshl_add_u64 v[56:57], s[12:13], 0, v[52:53]
	v_add_u32_e32 v50, 0xa0, v140
	v_lshl_add_u64 v[52:53], s[14:15], 0, v[52:53]
	v_lshl_add_u64 v[56:57], v[56:57], 0, s[54:55]
	v_ashrrev_i32_e32 v51, 31, v50
	v_lshl_add_u64 v[52:53], v[52:53], 0, s[54:55]
	v_lshl_add_u64 v[56:57], v[56:57], 0, v[138:139]
	v_lshl_add_u64 v[52:53], v[52:53], 0, v[138:139]
	v_fmamk_f32 v58, v236, 0x3b800000, v149
	v_rsq_f32_e32 v58, v58
	s_nop 0
	v_pk_mul_f32 v[36:37], v[36:37], v[58:59] op_sel_hi:[1,0]
	v_pk_mul_f32 v[34:35], v[34:35], v[58:59] op_sel_hi:[1,0]
	v_pk_mul_f32 v[40:41], v[40:41], v[58:59] op_sel_hi:[1,0]
	v_pk_mul_f32 v[38:39], v[38:39], v[58:59] op_sel_hi:[1,0]
	v_pk_mul_f32 v[44:45], v[44:45], v[58:59] op_sel_hi:[1,0]
	v_pk_mul_f32 v[42:43], v[42:43], v[58:59] op_sel_hi:[1,0]
	v_pk_mul_f32 v[48:49], v[48:49], v[58:59] op_sel_hi:[1,0]
	v_pk_mul_f32 v[46:47], v[46:47], v[58:59] op_sel_hi:[1,0]
	v_cvt_pk_bf16_f32 v34, v34, v35
	v_cvt_pk_bf16_f32 v35, v36, v37
	v_cvt_pk_bf16_f32 v36, v38, v39
	v_cvt_pk_bf16_f32 v37, v40, v41
	v_cvt_pk_bf16_f32 v38, v42, v43
	v_cvt_pk_bf16_f32 v39, v44, v45
	v_cvt_pk_bf16_f32 v40, v46, v47
	v_cvt_pk_bf16_f32 v41, v48, v49
	global_store_dwordx4 v[56:57], v[34:37], off
	global_store_dwordx4 v[52:53], v[38:41], off
	s_nop 0
	v_lshlrev_b64 v[36:37], 11, v[50:51]
	v_lshl_add_u64 v[40:41], s[12:13], 0, v[36:37]
	v_add_u32_e32 v34, 0xb0, v140
	v_lshl_add_u64 v[36:37], s[14:15], 0, v[36:37]
	v_lshl_add_u64 v[40:41], v[40:41], 0, s[54:55]
	v_ashrrev_i32_e32 v35, 31, v34
	v_lshl_add_u64 v[36:37], v[36:37], 0, s[54:55]
	v_lshl_add_u64 v[40:41], v[40:41], 0, v[138:139]
	v_lshl_add_u64 v[36:37], v[36:37], 0, v[138:139]
	v_fmamk_f32 v42, v237, 0x3b800000, v149
	v_rsq_f32_e32 v42, v42
	s_nop 0
	v_pk_mul_f32 v[20:21], v[20:21], v[42:43] op_sel_hi:[1,0]
	v_pk_mul_f32 v[18:19], v[18:19], v[42:43] op_sel_hi:[1,0]
	v_pk_mul_f32 v[24:25], v[24:25], v[42:43] op_sel_hi:[1,0]
	v_pk_mul_f32 v[22:23], v[22:23], v[42:43] op_sel_hi:[1,0]
	v_pk_mul_f32 v[28:29], v[28:29], v[42:43] op_sel_hi:[1,0]
	v_pk_mul_f32 v[26:27], v[26:27], v[42:43] op_sel_hi:[1,0]
	v_pk_mul_f32 v[32:33], v[32:33], v[42:43] op_sel_hi:[1,0]
	v_pk_mul_f32 v[30:31], v[30:31], v[42:43] op_sel_hi:[1,0]
	v_cvt_pk_bf16_f32 v18, v18, v19
	v_cvt_pk_bf16_f32 v19, v20, v21
	v_cvt_pk_bf16_f32 v20, v22, v23
	v_cvt_pk_bf16_f32 v21, v24, v25
	v_cvt_pk_bf16_f32 v22, v26, v27
	v_cvt_pk_bf16_f32 v23, v28, v29
	v_cvt_pk_bf16_f32 v24, v30, v31
	v_cvt_pk_bf16_f32 v25, v32, v33
	global_store_dwordx4 v[40:41], v[18:21], off
	global_store_dwordx4 v[36:37], v[22:25], off
	s_nop 0
	v_lshlrev_b64 v[18:19], 11, v[34:35]
	v_lshl_add_u64 v[20:21], s[12:13], 0, v[18:19]
	v_lshl_add_u64 v[18:19], s[14:15], 0, v[18:19]
	v_lshl_add_u64 v[20:21], v[20:21], 0, s[54:55]
	v_lshl_add_u64 v[18:19], v[18:19], 0, s[54:55]
	v_lshl_add_u64 v[20:21], v[20:21], 0, v[138:139]
	v_lshl_add_u64 v[18:19], v[18:19], 0, v[138:139]
	v_fmamk_f32 v22, v238, 0x3b800000, v149
	v_rsq_f32_e32 v22, v22
	s_nop 0
	v_pk_mul_f32 v[4:5], v[4:5], v[22:23] op_sel_hi:[1,0]
	v_pk_mul_f32 v[2:3], v[2:3], v[22:23] op_sel_hi:[1,0]
	v_pk_mul_f32 v[8:9], v[8:9], v[22:23] op_sel_hi:[1,0]
	v_pk_mul_f32 v[6:7], v[6:7], v[22:23] op_sel_hi:[1,0]
	v_pk_mul_f32 v[12:13], v[12:13], v[22:23] op_sel_hi:[1,0]
	v_pk_mul_f32 v[10:11], v[10:11], v[22:23] op_sel_hi:[1,0]
	v_pk_mul_f32 v[16:17], v[16:17], v[22:23] op_sel_hi:[1,0]
	v_pk_mul_f32 v[14:15], v[14:15], v[22:23] op_sel_hi:[1,0]
	v_cvt_pk_bf16_f32 v2, v2, v3
	v_cvt_pk_bf16_f32 v3, v4, v5
	v_cvt_pk_bf16_f32 v4, v6, v7
	v_cvt_pk_bf16_f32 v5, v8, v9
	v_cvt_pk_bf16_f32 v6, v10, v11
	v_cvt_pk_bf16_f32 v7, v12, v13
	v_cvt_pk_bf16_f32 v8, v14, v15
	v_cvt_pk_bf16_f32 v9, v16, v17
	global_store_dwordx4 v[20:21], v[2:5], off
	global_store_dwordx4 v[18:19], v[6:9], off
	s_cbranch_vccnz .LBB0_1389
	s_andn2_b64 vcc, exec, s[6:7]
	s_cbranch_vccnz .LBB0_1388
	s_barrier
	s_branch .LBB0_1388

.LBB0_1489:
	v_lshl_add_u32 v154, s78, 8, v141
	v_ashrrev_i32_e32 v155, 31, v154
	v_lshl_add_u64 v[152:153], v[154:155], 2, s[14:15]
	global_load_dword v232, v[152:153], off offset:64
	global_load_dword v233, v[152:153], off offset:128
	global_load_dword v234, v[152:153], off offset:192
	global_load_dword v235, v[152:153], off offset:512
	global_load_dword v236, v[152:153], off offset:576
	global_load_dword v237, v[152:153], off offset:640
	global_load_dword v238, v[152:153], off offset:704
	global_load_dword v138, v[152:153], off
	s_cmp_gt_i32 s77, 3
	s_cselect_b64 s[52:53], -1, 0
	s_lshl_b32 s50, s77, 8
	s_mov_b64 s[6:7], -1
	v_lshlrev_b32_e32 v152, 1, v140
	s_add_i32 s10, s63, s50
	s_and_b64 vcc, exec, s[52:53]
	s_waitcnt vmcnt(0)
	v_fmamk_f32 v138, v138, 0x3aaaaaab, v160
	v_rsq_f32_e32 v138, v138
	s_nop 0
	v_mul_f32_e32 v156, 0x3dd53b94, v138
	s_cbranch_vccz .LBB0_1491
	v_lshlrev_b32_e32 v138, 5, v154
	v_and_or_b32 v138, v138, s70, v140
	v_lshlrev_b32_e32 v138, 3, v138
	global_load_dwordx4 v[162:165], v138, s[26:27]
	global_load_dwordx4 v[166:169], v138, s[26:27] offset:16
	global_load_dwordx4 v[170:173], v138, s[26:27] offset:32
	global_load_dwordx4 v[174:177], v138, s[26:27] offset:48
	v_mov_b32_e32 v186, v128
	v_mov_b32_e32 v187, v121
	v_mov_b32_e32 v188, v120
	v_mov_b32_e32 v189, v129
	v_mov_b32_e32 v180, v118
	v_mov_b32_e32 v181, v127
	v_mov_b32_e32 v182, v122
	v_mov_b32_e32 v183, v115
	v_mov_b32_e32 v184, v114
	v_mov_b32_e32 v185, v123
	v_pk_mul_f32 v[186:187], v[186:187], v[156:157] op_sel_hi:[1,0]
	v_pk_mul_f32 v[188:189], v[188:189], v[156:157] op_sel_hi:[1,0]
	v_mov_b32_e32 v178, v126
	v_mov_b32_e32 v179, v119
	v_mov_b32_e32 v190, v124
	v_mov_b32_e32 v191, v117
	v_mov_b32_e32 v192, v116
	v_mov_b32_e32 v193, v125
	v_pk_mul_f32 v[180:181], v[180:181], v[156:157] op_sel_hi:[1,0]
	v_pk_mul_f32 v[182:183], v[182:183], v[156:157] op_sel_hi:[1,0]
	v_pk_mul_f32 v[184:185], v[184:185], v[156:157] op_sel_hi:[1,0]
	v_mov_b32_e32 v199, v189
	v_pk_mul_f32 v[178:179], v[178:179], v[156:157] op_sel_hi:[1,0]
	v_pk_mul_f32 v[190:191], v[190:191], v[156:157] op_sel_hi:[1,0]
	v_pk_mul_f32 v[192:193], v[192:193], v[156:157] op_sel_hi:[1,0]
	v_mov_b32_e32 v197, v185
	v_mov_b32_e32 v198, v186
	v_mov_b32_e32 v194, v178
	v_mov_b32_e32 v195, v181
	v_mov_b32_e32 v196, v182
	v_mov_b32_e32 v201, v193
	v_mov_b32_e32 v200, v190
	v_mov_b32_e32 v153, v139
	s_mov_b64 s[6:7], 0
	s_waitcnt vmcnt(3)
	v_mov_b32_e32 v210, v162
	v_mov_b32_e32 v212, v162
	s_waitcnt vmcnt(1)
	v_mov_b32_e32 v206, v171
	v_mov_b32_e32 v207, v172
	v_mov_b32_e32 v162, v170
	v_mov_b32_e32 v214, v170
	v_mov_b32_e32 v215, v172
	v_mov_b32_e32 v172, v171
	v_mov_b32_e32 v170, v166
	v_mov_b32_e32 v171, v169
	v_mov_b32_e32 v202, v163
	v_mov_b32_e32 v203, v164
	v_mov_b32_e32 v205, v168
	v_mov_b32_e32 v211, v165
	v_mov_b32_e32 v213, v164
	v_mov_b32_e32 v164, v163
	v_mov_b32_e32 v163, v173
	v_mov_b32_e32 v217, v168
	v_mov_b32_e32 v168, v167
	v_pk_mul_f32 v[170:171], v[188:189], v[170:171]
	v_mov_b32_e32 v189, v187
	v_mov_b32_e32 v204, v167
	s_waitcnt vmcnt(0)
	v_mov_b32_e32 v208, v175
	v_mov_b32_e32 v209, v176
	v_mov_b32_e32 v216, v166
	v_mov_b32_e32 v166, v174
	v_mov_b32_e32 v167, v177
	v_mov_b32_e32 v218, v174
	v_mov_b32_e32 v219, v176
	v_mov_b32_e32 v176, v175
	v_pk_mul_f32 v[174:175], v[180:181], v[210:211]
	v_pk_mul_f32 v[162:163], v[184:185], v[162:163]
	v_mov_b32_e32 v185, v183
	v_pk_mul_f32 v[168:169], v[188:189], v[168:169]
	v_mov_b32_e32 v181, v179
	v_pk_mul_f32 v[166:167], v[192:193], v[166:167]
	v_mov_b32_e32 v193, v191
	v_pk_fma_f32 v[174:175], v[178:179], v[202:203], v[174:175]
	v_pk_fma_f32 v[178:179], v[182:183], v[206:207], v[162:163]
	v_pk_mul_f32 v[162:163], v[184:185], v[172:173]
	v_pk_fma_f32 v[168:169], v[198:199], v[216:217], v[168:169] neg_lo:[0,0,1] neg_hi:[0,0,1]
	v_pk_mul_f32 v[172:173], v[192:193], v[176:177]
	v_pk_fma_f32 v[176:177], v[196:197], v[214:215], v[162:163] neg_lo:[0,0,1] neg_hi:[0,0,1]
	v_cvt_pk_bf16_f32 v163, v168, v169
	v_lshlrev_b64 v[168:169], 10, v[154:155]
	v_pk_mul_f32 v[164:165], v[180:181], v[164:165]
	v_lshl_add_u64 v[168:169], s[24:25], 0, v[168:169]
	v_pk_fma_f32 v[164:165], v[194:195], v[212:213], v[164:165] neg_lo:[0,0,1] neg_hi:[0,0,1]
	v_pk_fma_f32 v[172:173], v[200:201], v[218:219], v[172:173] neg_lo:[0,0,1] neg_hi:[0,0,1]
	v_lshl_add_u64 v[168:169], s[10:11], 1, v[168:169]
	v_pk_fma_f32 v[170:171], v[186:187], v[204:205], v[170:171]
	v_pk_fma_f32 v[166:167], v[190:191], v[208:209], v[166:167]
	v_cvt_pk_bf16_f32 v162, v164, v165
	v_cvt_pk_bf16_f32 v164, v176, v177
	v_cvt_pk_bf16_f32 v165, v172, v173
	v_lshl_add_u64 v[168:169], v[168:169], 0, v[152:153]
	global_store_dwordx4 v[168:169], v[162:165], off
	s_nop 1
	v_cvt_pk_bf16_f32 v162, v174, v175
	v_cvt_pk_bf16_f32 v163, v170, v171
	v_cvt_pk_bf16_f32 v164, v178, v179
	v_cvt_pk_bf16_f32 v165, v166, v167
	global_store_dwordx4 v[168:169], v[162:165], off offset:64

.LBB0_1493:
	s_nop 1
	v_or_b32_e32 v116, 16, v154
	v_ashrrev_i32_e32 v117, 31, v116
	v_cndmask_b32_e64 v115, 0, 1, s[52:53]
	v_cmp_ne_u32_e64 s[6:7], 1, v115
	s_andn2_b64 vcc, exec, s[52:53]
	s_mov_b64 s[52:53], -1
	v_fmamk_f32 v114, v232, 0x3aaaaaab, v160
	v_rsq_f32_e32 v114, v114
	s_nop 0
	v_mul_f32_e32 v114, 0x3dd53b94, v114
	s_cbranch_vccnz .LBB0_1495
	v_lshlrev_b32_e32 v115, 5, v116
	v_and_or_b32 v115, v115, s71, v140
	v_lshlrev_b32_e32 v115, 3, v115
	global_load_dwordx4 v[118:121], v115, s[26:27]
	global_load_dwordx4 v[122:125], v115, s[26:27] offset:16
	global_load_dwordx4 v[126:129], v115, s[26:27] offset:32
	global_load_dwordx4 v[162:165], v115, s[26:27] offset:48
	v_mov_b32_e32 v174, v112
	v_mov_b32_e32 v175, v105
	v_mov_b32_e32 v176, v104
	v_mov_b32_e32 v177, v113
	v_mov_b32_e32 v168, v102
	v_mov_b32_e32 v169, v111
	v_mov_b32_e32 v170, v106
	v_mov_b32_e32 v171, v99
	v_mov_b32_e32 v172, v98
	v_mov_b32_e32 v173, v107
	v_pk_mul_f32 v[174:175], v[174:175], v[114:115] op_sel_hi:[1,0]
	v_pk_mul_f32 v[176:177], v[176:177], v[114:115] op_sel_hi:[1,0]
	v_mov_b32_e32 v166, v110
	v_mov_b32_e32 v167, v103
	v_mov_b32_e32 v178, v108
	v_mov_b32_e32 v179, v101
	v_mov_b32_e32 v180, v100
	v_mov_b32_e32 v181, v109
	v_pk_mul_f32 v[168:169], v[168:169], v[114:115] op_sel_hi:[1,0]
	v_pk_mul_f32 v[170:171], v[170:171], v[114:115] op_sel_hi:[1,0]
	v_pk_mul_f32 v[172:173], v[172:173], v[114:115] op_sel_hi:[1,0]
	v_mov_b32_e32 v187, v177
	v_pk_mul_f32 v[166:167], v[166:167], v[114:115] op_sel_hi:[1,0]
	v_pk_mul_f32 v[178:179], v[178:179], v[114:115] op_sel_hi:[1,0]
	v_pk_mul_f32 v[180:181], v[180:181], v[114:115] op_sel_hi:[1,0]
	v_mov_b32_e32 v185, v173
	v_mov_b32_e32 v186, v174
	v_mov_b32_e32 v182, v166
	v_mov_b32_e32 v183, v169
	v_mov_b32_e32 v184, v170
	v_mov_b32_e32 v189, v181
	v_mov_b32_e32 v188, v178
	v_mov_b32_e32 v153, v139
	s_mov_b64 s[52:53], 0
	s_waitcnt vmcnt(3)
	v_mov_b32_e32 v198, v118
	v_mov_b32_e32 v200, v118
	s_waitcnt vmcnt(1)
	v_mov_b32_e32 v194, v127
	v_mov_b32_e32 v195, v128
	v_mov_b32_e32 v118, v126
	v_mov_b32_e32 v202, v126
	v_mov_b32_e32 v203, v128
	v_mov_b32_e32 v128, v127
	v_mov_b32_e32 v126, v122
	v_mov_b32_e32 v127, v125
	v_mov_b32_e32 v190, v119
	v_mov_b32_e32 v191, v120
	v_mov_b32_e32 v193, v124
	v_mov_b32_e32 v199, v121
	v_mov_b32_e32 v201, v120
	v_mov_b32_e32 v120, v119
	v_mov_b32_e32 v119, v129
	v_mov_b32_e32 v205, v124
	v_mov_b32_e32 v124, v123
	v_pk_mul_f32 v[126:127], v[176:177], v[126:127]
	v_mov_b32_e32 v177, v175
	v_mov_b32_e32 v192, v123
	s_waitcnt vmcnt(0)
	v_mov_b32_e32 v196, v163
	v_mov_b32_e32 v197, v164
	v_mov_b32_e32 v204, v122
	v_mov_b32_e32 v122, v162
	v_mov_b32_e32 v123, v165
	v_mov_b32_e32 v206, v162
	v_mov_b32_e32 v207, v164
	v_mov_b32_e32 v164, v163
	v_pk_mul_f32 v[162:163], v[168:169], v[198:199]
	v_pk_mul_f32 v[118:119], v[172:173], v[118:119]
	v_mov_b32_e32 v173, v171
	v_pk_mul_f32 v[124:125], v[176:177], v[124:125]
	v_mov_b32_e32 v169, v167
	v_pk_mul_f32 v[122:123], v[180:181], v[122:123]
	v_mov_b32_e32 v181, v179
	v_pk_fma_f32 v[162:163], v[166:167], v[190:191], v[162:163]
	v_pk_fma_f32 v[166:167], v[170:171], v[194:195], v[118:119]
	v_pk_mul_f32 v[118:119], v[172:173], v[128:129]
	v_pk_fma_f32 v[124:125], v[186:187], v[204:205], v[124:125] neg_lo:[0,0,1] neg_hi:[0,0,1]
	v_pk_mul_f32 v[128:129], v[180:181], v[164:165]
	v_pk_fma_f32 v[164:165], v[184:185], v[202:203], v[118:119] neg_lo:[0,0,1] neg_hi:[0,0,1]
	v_cvt_pk_bf16_f32 v119, v124, v125
	v_lshlrev_b64 v[124:125], 10, v[116:117]
	v_pk_mul_f32 v[120:121], v[168:169], v[120:121]
	v_lshl_add_u64 v[124:125], s[24:25], 0, v[124:125]
	v_pk_fma_f32 v[120:121], v[182:183], v[200:201], v[120:121] neg_lo:[0,0,1] neg_hi:[0,0,1]
	v_pk_fma_f32 v[128:129], v[188:189], v[206:207], v[128:129] neg_lo:[0,0,1] neg_hi:[0,0,1]
	v_lshl_add_u64 v[124:125], s[10:11], 1, v[124:125]
	v_pk_fma_f32 v[126:127], v[174:175], v[192:193], v[126:127]
	v_pk_fma_f32 v[122:123], v[178:179], v[196:197], v[122:123]
	v_cvt_pk_bf16_f32 v118, v120, v121
	v_cvt_pk_bf16_f32 v120, v164, v165
	v_cvt_pk_bf16_f32 v121, v128, v129
	v_lshl_add_u64 v[124:125], v[124:125], 0, v[152:153]
	global_store_dwordx4 v[124:125], v[118:121], off
	s_nop 1
	v_cvt_pk_bf16_f32 v118, v162, v163
	v_cvt_pk_bf16_f32 v119, v126, v127
	v_cvt_pk_bf16_f32 v120, v166, v167
	v_cvt_pk_bf16_f32 v121, v122, v123
	global_store_dwordx4 v[124:125], v[118:121], off offset:64

.LBB0_1497:
	s_nop 1
	v_or_b32_e32 v100, 32, v154
	v_ashrrev_i32_e32 v101, 31, v100
	s_and_b64 vcc, exec, s[6:7]
	s_mov_b64 s[52:53], -1
	v_fmamk_f32 v98, v233, 0x3aaaaaab, v160
	v_rsq_f32_e32 v98, v98
	s_nop 0
	v_mul_f32_e32 v98, 0x3dd53b94, v98
	s_cbranch_vccnz .LBB0_1499
	v_lshlrev_b32_e32 v99, 5, v100
	v_and_or_b32 v99, v99, s72, v140
	v_lshlrev_b32_e32 v99, 3, v99
	global_load_dwordx4 v[102:105], v99, s[26:27]
	global_load_dwordx4 v[106:109], v99, s[26:27] offset:16
	global_load_dwordx4 v[110:113], v99, s[26:27] offset:32
	global_load_dwordx4 v[114:117], v99, s[26:27] offset:48
	v_mov_b32_e32 v126, v96
	v_mov_b32_e32 v127, v89
	v_mov_b32_e32 v128, v88
	v_mov_b32_e32 v129, v97
	v_mov_b32_e32 v120, v86
	v_mov_b32_e32 v121, v95
	v_mov_b32_e32 v122, v90
	v_mov_b32_e32 v123, v83
	v_mov_b32_e32 v124, v82
	v_mov_b32_e32 v125, v91
	v_pk_mul_f32 v[126:127], v[126:127], v[98:99] op_sel_hi:[1,0]
	v_pk_mul_f32 v[128:129], v[128:129], v[98:99] op_sel_hi:[1,0]
	v_mov_b32_e32 v118, v94
	v_mov_b32_e32 v119, v87
	v_mov_b32_e32 v162, v92
	v_mov_b32_e32 v163, v85
	v_mov_b32_e32 v164, v84
	v_mov_b32_e32 v165, v93
	v_pk_mul_f32 v[120:121], v[120:121], v[98:99] op_sel_hi:[1,0]
	v_pk_mul_f32 v[122:123], v[122:123], v[98:99] op_sel_hi:[1,0]
	v_pk_mul_f32 v[124:125], v[124:125], v[98:99] op_sel_hi:[1,0]
	v_mov_b32_e32 v171, v129
	v_pk_mul_f32 v[118:119], v[118:119], v[98:99] op_sel_hi:[1,0]
	v_pk_mul_f32 v[162:163], v[162:163], v[98:99] op_sel_hi:[1,0]
	v_pk_mul_f32 v[164:165], v[164:165], v[98:99] op_sel_hi:[1,0]
	v_mov_b32_e32 v169, v125
	v_mov_b32_e32 v170, v126
	v_mov_b32_e32 v166, v118
	v_mov_b32_e32 v167, v121
	v_mov_b32_e32 v168, v122
	v_mov_b32_e32 v173, v165
	v_mov_b32_e32 v172, v162
	v_mov_b32_e32 v153, v139
	s_mov_b64 s[52:53], 0
	s_waitcnt vmcnt(3)
	v_mov_b32_e32 v182, v102
	v_mov_b32_e32 v184, v102
	s_waitcnt vmcnt(1)
	v_mov_b32_e32 v178, v111
	v_mov_b32_e32 v179, v112
	v_mov_b32_e32 v102, v110
	v_mov_b32_e32 v186, v110
	v_mov_b32_e32 v187, v112
	v_mov_b32_e32 v112, v111
	v_mov_b32_e32 v110, v106
	v_mov_b32_e32 v111, v109
	v_mov_b32_e32 v174, v103
	v_mov_b32_e32 v175, v104
	v_mov_b32_e32 v177, v108
	v_mov_b32_e32 v183, v105
	v_mov_b32_e32 v185, v104
	v_mov_b32_e32 v104, v103
	v_mov_b32_e32 v103, v113
	v_mov_b32_e32 v189, v108
	v_mov_b32_e32 v108, v107
	v_pk_mul_f32 v[110:111], v[128:129], v[110:111]
	v_mov_b32_e32 v129, v127
	v_mov_b32_e32 v176, v107
	s_waitcnt vmcnt(0)
	v_mov_b32_e32 v180, v115
	v_mov_b32_e32 v181, v116
	v_mov_b32_e32 v188, v106
	v_mov_b32_e32 v106, v114
	v_mov_b32_e32 v107, v117
	v_mov_b32_e32 v190, v114
	v_mov_b32_e32 v191, v116
	v_mov_b32_e32 v116, v115
	v_pk_mul_f32 v[114:115], v[120:121], v[182:183]
	v_pk_mul_f32 v[102:103], v[124:125], v[102:103]
	v_mov_b32_e32 v125, v123
	v_pk_mul_f32 v[108:109], v[128:129], v[108:109]
	v_mov_b32_e32 v121, v119
	v_pk_mul_f32 v[106:107], v[164:165], v[106:107]
	v_mov_b32_e32 v165, v163
	v_pk_fma_f32 v[114:115], v[118:119], v[174:175], v[114:115]
	v_pk_fma_f32 v[118:119], v[122:123], v[178:179], v[102:103]
	v_pk_mul_f32 v[102:103], v[124:125], v[112:113]
	v_pk_fma_f32 v[108:109], v[170:171], v[188:189], v[108:109] neg_lo:[0,0,1] neg_hi:[0,0,1]
	v_pk_mul_f32 v[112:113], v[164:165], v[116:117]
	v_pk_fma_f32 v[116:117], v[168:169], v[186:187], v[102:103] neg_lo:[0,0,1] neg_hi:[0,0,1]
	v_cvt_pk_bf16_f32 v103, v108, v109
	v_lshlrev_b64 v[108:109], 10, v[100:101]
	v_pk_mul_f32 v[104:105], v[120:121], v[104:105]
	v_lshl_add_u64 v[108:109], s[24:25], 0, v[108:109]
	v_pk_fma_f32 v[104:105], v[166:167], v[184:185], v[104:105] neg_lo:[0,0,1] neg_hi:[0,0,1]
	v_pk_fma_f32 v[112:113], v[172:173], v[190:191], v[112:113] neg_lo:[0,0,1] neg_hi:[0,0,1]
	v_lshl_add_u64 v[108:109], s[10:11], 1, v[108:109]
	v_pk_fma_f32 v[110:111], v[126:127], v[176:177], v[110:111]
	v_pk_fma_f32 v[106:107], v[162:163], v[180:181], v[106:107]
	v_cvt_pk_bf16_f32 v102, v104, v105
	v_cvt_pk_bf16_f32 v104, v116, v117
	v_cvt_pk_bf16_f32 v105, v112, v113
	v_lshl_add_u64 v[108:109], v[108:109], 0, v[152:153]
	global_store_dwordx4 v[108:109], v[102:105], off
	s_nop 1
	v_cvt_pk_bf16_f32 v102, v114, v115
	v_cvt_pk_bf16_f32 v103, v110, v111
	v_cvt_pk_bf16_f32 v104, v118, v119
	v_cvt_pk_bf16_f32 v105, v106, v107
	global_store_dwordx4 v[108:109], v[102:105], off offset:64

.LBB0_1501:
	s_nop 1
	v_or_b32_e32 v84, 48, v154
	v_ashrrev_i32_e32 v85, 31, v84
	s_and_b64 vcc, exec, s[6:7]
	s_mov_b64 s[52:53], -1
	v_fmamk_f32 v82, v234, 0x3aaaaaab, v160
	v_rsq_f32_e32 v82, v82
	s_nop 0
	v_mul_f32_e32 v82, 0x3dd53b94, v82
	s_cbranch_vccnz .LBB0_1503
	v_lshlrev_b32_e32 v83, 5, v84
	v_and_or_b32 v83, v83, s73, v140
	v_lshlrev_b32_e32 v83, 3, v83
	global_load_dwordx4 v[86:89], v83, s[26:27]
	global_load_dwordx4 v[90:93], v83, s[26:27] offset:16
	global_load_dwordx4 v[94:97], v83, s[26:27] offset:32
	global_load_dwordx4 v[98:101], v83, s[26:27] offset:48
	v_mov_b32_e32 v110, v80
	v_mov_b32_e32 v111, v73
	v_mov_b32_e32 v112, v72
	v_mov_b32_e32 v113, v81
	v_mov_b32_e32 v104, v70
	v_mov_b32_e32 v105, v79
	v_mov_b32_e32 v106, v74
	v_mov_b32_e32 v107, v67
	v_mov_b32_e32 v108, v66
	v_mov_b32_e32 v109, v75
	v_pk_mul_f32 v[110:111], v[110:111], v[82:83] op_sel_hi:[1,0]
	v_pk_mul_f32 v[112:113], v[112:113], v[82:83] op_sel_hi:[1,0]
	v_mov_b32_e32 v102, v78
	v_mov_b32_e32 v103, v71
	v_mov_b32_e32 v114, v76
	v_mov_b32_e32 v115, v69
	v_mov_b32_e32 v116, v68
	v_mov_b32_e32 v117, v77
	v_pk_mul_f32 v[104:105], v[104:105], v[82:83] op_sel_hi:[1,0]
	v_pk_mul_f32 v[106:107], v[106:107], v[82:83] op_sel_hi:[1,0]
	v_pk_mul_f32 v[108:109], v[108:109], v[82:83] op_sel_hi:[1,0]
	v_mov_b32_e32 v123, v113
	v_pk_mul_f32 v[102:103], v[102:103], v[82:83] op_sel_hi:[1,0]
	v_pk_mul_f32 v[114:115], v[114:115], v[82:83] op_sel_hi:[1,0]
	v_pk_mul_f32 v[116:117], v[116:117], v[82:83] op_sel_hi:[1,0]
	v_mov_b32_e32 v121, v109
	v_mov_b32_e32 v122, v110
	v_mov_b32_e32 v118, v102
	v_mov_b32_e32 v119, v105
	v_mov_b32_e32 v120, v106
	v_mov_b32_e32 v125, v117
	v_mov_b32_e32 v124, v114
	v_mov_b32_e32 v153, v139
	s_mov_b64 s[52:53], 0
	s_waitcnt vmcnt(3)
	v_mov_b32_e32 v166, v86
	v_mov_b32_e32 v168, v86
	s_waitcnt vmcnt(1)
	v_mov_b32_e32 v162, v95
	v_mov_b32_e32 v163, v96
	v_mov_b32_e32 v86, v94
	v_mov_b32_e32 v170, v94
	v_mov_b32_e32 v171, v96
	v_mov_b32_e32 v96, v95
	v_mov_b32_e32 v94, v90
	v_mov_b32_e32 v95, v93
	v_mov_b32_e32 v126, v87
	v_mov_b32_e32 v127, v88
	v_mov_b32_e32 v129, v92
	v_mov_b32_e32 v167, v89
	v_mov_b32_e32 v169, v88
	v_mov_b32_e32 v88, v87
	v_mov_b32_e32 v87, v97
	v_mov_b32_e32 v173, v92
	v_mov_b32_e32 v92, v91
	v_pk_mul_f32 v[94:95], v[112:113], v[94:95]
	v_mov_b32_e32 v113, v111
	v_mov_b32_e32 v128, v91
	s_waitcnt vmcnt(0)
	v_mov_b32_e32 v164, v99
	v_mov_b32_e32 v165, v100
	v_mov_b32_e32 v172, v90
	v_mov_b32_e32 v90, v98
	v_mov_b32_e32 v91, v101
	v_mov_b32_e32 v174, v98
	v_mov_b32_e32 v175, v100
	v_mov_b32_e32 v100, v99
	v_pk_mul_f32 v[98:99], v[104:105], v[166:167]
	v_pk_mul_f32 v[86:87], v[108:109], v[86:87]
	v_mov_b32_e32 v109, v107
	v_pk_mul_f32 v[92:93], v[112:113], v[92:93]
	v_mov_b32_e32 v105, v103
	v_pk_mul_f32 v[90:91], v[116:117], v[90:91]
	v_mov_b32_e32 v117, v115
	v_pk_fma_f32 v[98:99], v[102:103], v[126:127], v[98:99]
	v_pk_fma_f32 v[102:103], v[106:107], v[162:163], v[86:87]
	v_pk_mul_f32 v[86:87], v[108:109], v[96:97]
	v_pk_fma_f32 v[92:93], v[122:123], v[172:173], v[92:93] neg_lo:[0,0,1] neg_hi:[0,0,1]
	v_pk_mul_f32 v[96:97], v[116:117], v[100:101]
	v_pk_fma_f32 v[100:101], v[120:121], v[170:171], v[86:87] neg_lo:[0,0,1] neg_hi:[0,0,1]
	v_cvt_pk_bf16_f32 v87, v92, v93
	v_lshlrev_b64 v[92:93], 10, v[84:85]
	v_pk_mul_f32 v[88:89], v[104:105], v[88:89]
	v_lshl_add_u64 v[92:93], s[24:25], 0, v[92:93]
	v_pk_fma_f32 v[88:89], v[118:119], v[168:169], v[88:89] neg_lo:[0,0,1] neg_hi:[0,0,1]
	v_pk_fma_f32 v[96:97], v[124:125], v[174:175], v[96:97] neg_lo:[0,0,1] neg_hi:[0,0,1]
	v_lshl_add_u64 v[92:93], s[10:11], 1, v[92:93]
	v_pk_fma_f32 v[94:95], v[110:111], v[128:129], v[94:95]
	v_pk_fma_f32 v[90:91], v[114:115], v[164:165], v[90:91]
	v_cvt_pk_bf16_f32 v86, v88, v89
	v_cvt_pk_bf16_f32 v88, v100, v101
	v_cvt_pk_bf16_f32 v89, v96, v97
	v_lshl_add_u64 v[92:93], v[92:93], 0, v[152:153]
	global_store_dwordx4 v[92:93], v[86:89], off
	s_nop 1
	v_cvt_pk_bf16_f32 v86, v98, v99
	v_cvt_pk_bf16_f32 v87, v94, v95
	v_cvt_pk_bf16_f32 v88, v102, v103
	v_cvt_pk_bf16_f32 v89, v90, v91
	global_store_dwordx4 v[92:93], v[86:89], off offset:64

.LBB0_1505:
	s_nop 1
	v_add_u32_e32 v68, 0x80, v154
	v_ashrrev_i32_e32 v69, 31, v68
	s_and_b64 vcc, exec, s[6:7]
	s_mov_b64 s[52:53], -1
	v_fmamk_f32 v66, v235, 0x3aaaaaab, v160
	v_rsq_f32_e32 v66, v66
	s_nop 0
	v_mul_f32_e32 v66, 0x3dd53b94, v66
	s_cbranch_vccnz .LBB0_1507
	v_lshlrev_b32_e32 v67, 5, v68
	v_and_or_b32 v67, v67, s70, v140
	v_lshlrev_b32_e32 v67, 3, v67
	global_load_dwordx4 v[70:73], v67, s[26:27]
	global_load_dwordx4 v[74:77], v67, s[26:27] offset:16
	global_load_dwordx4 v[78:81], v67, s[26:27] offset:32
	global_load_dwordx4 v[82:85], v67, s[26:27] offset:48
	v_mov_b32_e32 v94, v64
	v_mov_b32_e32 v95, v57
	v_mov_b32_e32 v96, v56
	v_mov_b32_e32 v97, v65
	v_mov_b32_e32 v88, v54
	v_mov_b32_e32 v89, v63
	v_mov_b32_e32 v90, v58
	v_mov_b32_e32 v91, v51
	v_mov_b32_e32 v92, v50
	v_mov_b32_e32 v93, v59
	v_pk_mul_f32 v[94:95], v[94:95], v[66:67] op_sel_hi:[1,0]
	v_pk_mul_f32 v[96:97], v[96:97], v[66:67] op_sel_hi:[1,0]
	v_mov_b32_e32 v86, v62
	v_mov_b32_e32 v87, v55
	v_mov_b32_e32 v98, v60
	v_mov_b32_e32 v99, v53
	v_mov_b32_e32 v100, v52
	v_mov_b32_e32 v101, v61
	v_pk_mul_f32 v[88:89], v[88:89], v[66:67] op_sel_hi:[1,0]
	v_pk_mul_f32 v[90:91], v[90:91], v[66:67] op_sel_hi:[1,0]
	v_pk_mul_f32 v[92:93], v[92:93], v[66:67] op_sel_hi:[1,0]
	v_mov_b32_e32 v107, v97
	v_pk_mul_f32 v[86:87], v[86:87], v[66:67] op_sel_hi:[1,0]
	v_pk_mul_f32 v[98:99], v[98:99], v[66:67] op_sel_hi:[1,0]
	v_pk_mul_f32 v[100:101], v[100:101], v[66:67] op_sel_hi:[1,0]
	v_mov_b32_e32 v105, v93
	v_mov_b32_e32 v106, v94
	v_mov_b32_e32 v102, v86
	v_mov_b32_e32 v103, v89
	v_mov_b32_e32 v104, v90
	v_mov_b32_e32 v109, v101
	v_mov_b32_e32 v108, v98
	v_mov_b32_e32 v153, v139
	s_mov_b64 s[52:53], 0
	s_waitcnt vmcnt(3)
	v_mov_b32_e32 v118, v70
	v_mov_b32_e32 v120, v70
	s_waitcnt vmcnt(1)
	v_mov_b32_e32 v114, v79
	v_mov_b32_e32 v115, v80
	v_mov_b32_e32 v70, v78
	v_mov_b32_e32 v122, v78
	v_mov_b32_e32 v123, v80
	v_mov_b32_e32 v80, v79
	v_mov_b32_e32 v78, v74
	v_mov_b32_e32 v79, v77
	v_mov_b32_e32 v110, v71
	v_mov_b32_e32 v111, v72
	v_mov_b32_e32 v113, v76
	v_mov_b32_e32 v119, v73
	v_mov_b32_e32 v121, v72
	v_mov_b32_e32 v72, v71
	v_mov_b32_e32 v71, v81
	v_mov_b32_e32 v125, v76
	v_mov_b32_e32 v76, v75
	v_pk_mul_f32 v[78:79], v[96:97], v[78:79]
	v_mov_b32_e32 v97, v95
	v_mov_b32_e32 v112, v75
	s_waitcnt vmcnt(0)
	v_mov_b32_e32 v116, v83
	v_mov_b32_e32 v117, v84
	v_mov_b32_e32 v124, v74
	v_mov_b32_e32 v74, v82
	v_mov_b32_e32 v75, v85
	v_mov_b32_e32 v126, v82
	v_mov_b32_e32 v127, v84
	v_mov_b32_e32 v84, v83
	v_pk_mul_f32 v[82:83], v[88:89], v[118:119]
	v_pk_mul_f32 v[70:71], v[92:93], v[70:71]
	v_mov_b32_e32 v93, v91
	v_pk_mul_f32 v[76:77], v[96:97], v[76:77]
	v_mov_b32_e32 v89, v87
	v_pk_mul_f32 v[74:75], v[100:101], v[74:75]
	v_mov_b32_e32 v101, v99
	v_pk_fma_f32 v[82:83], v[86:87], v[110:111], v[82:83]
	v_pk_fma_f32 v[86:87], v[90:91], v[114:115], v[70:71]
	v_pk_mul_f32 v[70:71], v[92:93], v[80:81]
	v_pk_fma_f32 v[76:77], v[106:107], v[124:125], v[76:77] neg_lo:[0,0,1] neg_hi:[0,0,1]
	v_pk_mul_f32 v[80:81], v[100:101], v[84:85]
	v_pk_fma_f32 v[84:85], v[104:105], v[122:123], v[70:71] neg_lo:[0,0,1] neg_hi:[0,0,1]
	v_cvt_pk_bf16_f32 v71, v76, v77
	v_lshlrev_b64 v[76:77], 10, v[68:69]
	v_pk_mul_f32 v[72:73], v[88:89], v[72:73]
	v_lshl_add_u64 v[76:77], s[24:25], 0, v[76:77]
	v_pk_fma_f32 v[72:73], v[102:103], v[120:121], v[72:73] neg_lo:[0,0,1] neg_hi:[0,0,1]
	v_pk_fma_f32 v[80:81], v[108:109], v[126:127], v[80:81] neg_lo:[0,0,1] neg_hi:[0,0,1]
	v_lshl_add_u64 v[76:77], s[10:11], 1, v[76:77]
	v_pk_fma_f32 v[78:79], v[94:95], v[112:113], v[78:79]
	v_pk_fma_f32 v[74:75], v[98:99], v[116:117], v[74:75]
	v_cvt_pk_bf16_f32 v70, v72, v73
	v_cvt_pk_bf16_f32 v72, v84, v85
	v_cvt_pk_bf16_f32 v73, v80, v81
	v_lshl_add_u64 v[76:77], v[76:77], 0, v[152:153]
	global_store_dwordx4 v[76:77], v[70:73], off
	s_nop 1
	v_cvt_pk_bf16_f32 v70, v82, v83
	v_cvt_pk_bf16_f32 v71, v78, v79
	v_cvt_pk_bf16_f32 v72, v86, v87
	v_cvt_pk_bf16_f32 v73, v74, v75
	global_store_dwordx4 v[76:77], v[70:73], off offset:64

.LBB0_1509:
	s_nop 1
	v_add_u32_e32 v52, 0x90, v154
	v_ashrrev_i32_e32 v53, 31, v52
	s_and_b64 vcc, exec, s[6:7]
	s_mov_b64 s[52:53], -1
	v_fmamk_f32 v50, v236, 0x3aaaaaab, v160
	v_rsq_f32_e32 v50, v50
	s_nop 0
	v_mul_f32_e32 v50, 0x3dd53b94, v50
	s_cbranch_vccnz .LBB0_1511
	v_lshlrev_b32_e32 v51, 5, v52
	v_and_or_b32 v51, v51, s71, v140
	v_lshlrev_b32_e32 v51, 3, v51
	global_load_dwordx4 v[54:57], v51, s[26:27]
	global_load_dwordx4 v[58:61], v51, s[26:27] offset:16
	global_load_dwordx4 v[62:65], v51, s[26:27] offset:32
	global_load_dwordx4 v[66:69], v51, s[26:27] offset:48
	v_mov_b32_e32 v78, v48
	v_mov_b32_e32 v79, v41
	v_mov_b32_e32 v80, v40
	v_mov_b32_e32 v81, v49
	v_mov_b32_e32 v72, v38
	v_mov_b32_e32 v73, v47
	v_mov_b32_e32 v74, v42
	v_mov_b32_e32 v75, v35
	v_mov_b32_e32 v76, v34
	v_mov_b32_e32 v77, v43
	v_pk_mul_f32 v[78:79], v[78:79], v[50:51] op_sel_hi:[1,0]
	v_pk_mul_f32 v[80:81], v[80:81], v[50:51] op_sel_hi:[1,0]
	v_mov_b32_e32 v70, v46
	v_mov_b32_e32 v71, v39
	v_mov_b32_e32 v82, v44
	v_mov_b32_e32 v83, v37
	v_mov_b32_e32 v84, v36
	v_mov_b32_e32 v85, v45
	v_pk_mul_f32 v[72:73], v[72:73], v[50:51] op_sel_hi:[1,0]
	v_pk_mul_f32 v[74:75], v[74:75], v[50:51] op_sel_hi:[1,0]
	v_pk_mul_f32 v[76:77], v[76:77], v[50:51] op_sel_hi:[1,0]
	v_mov_b32_e32 v91, v81
	v_pk_mul_f32 v[70:71], v[70:71], v[50:51] op_sel_hi:[1,0]
	v_pk_mul_f32 v[82:83], v[82:83], v[50:51] op_sel_hi:[1,0]
	v_pk_mul_f32 v[84:85], v[84:85], v[50:51] op_sel_hi:[1,0]
	v_mov_b32_e32 v89, v77
	v_mov_b32_e32 v90, v78
	v_mov_b32_e32 v86, v70
	v_mov_b32_e32 v87, v73
	v_mov_b32_e32 v88, v74
	v_mov_b32_e32 v93, v85
	v_mov_b32_e32 v92, v82
	v_mov_b32_e32 v153, v139
	s_mov_b64 s[52:53], 0
	s_waitcnt vmcnt(3)
	v_mov_b32_e32 v102, v54
	v_mov_b32_e32 v104, v54
	s_waitcnt vmcnt(1)
	v_mov_b32_e32 v98, v63
	v_mov_b32_e32 v99, v64
	v_mov_b32_e32 v54, v62
	v_mov_b32_e32 v106, v62
	v_mov_b32_e32 v107, v64
	v_mov_b32_e32 v64, v63
	v_mov_b32_e32 v62, v58
	v_mov_b32_e32 v63, v61
	v_mov_b32_e32 v94, v55
	v_mov_b32_e32 v95, v56
	v_mov_b32_e32 v97, v60
	v_mov_b32_e32 v103, v57
	v_mov_b32_e32 v105, v56
	v_mov_b32_e32 v56, v55
	v_mov_b32_e32 v55, v65
	v_mov_b32_e32 v109, v60
	v_mov_b32_e32 v60, v59
	v_pk_mul_f32 v[62:63], v[80:81], v[62:63]
	v_mov_b32_e32 v81, v79
	v_mov_b32_e32 v96, v59
	s_waitcnt vmcnt(0)
	v_mov_b32_e32 v100, v67
	v_mov_b32_e32 v101, v68
	v_mov_b32_e32 v108, v58
	v_mov_b32_e32 v58, v66
	v_mov_b32_e32 v59, v69
	v_mov_b32_e32 v110, v66
	v_mov_b32_e32 v111, v68
	v_mov_b32_e32 v68, v67
	v_pk_mul_f32 v[66:67], v[72:73], v[102:103]
	v_pk_mul_f32 v[54:55], v[76:77], v[54:55]
	v_mov_b32_e32 v77, v75
	v_pk_mul_f32 v[60:61], v[80:81], v[60:61]
	v_mov_b32_e32 v73, v71
	v_pk_mul_f32 v[58:59], v[84:85], v[58:59]
	v_mov_b32_e32 v85, v83
	v_pk_fma_f32 v[66:67], v[70:71], v[94:95], v[66:67]
	v_pk_fma_f32 v[70:71], v[74:75], v[98:99], v[54:55]
	v_pk_mul_f32 v[54:55], v[76:77], v[64:65]
	v_pk_fma_f32 v[60:61], v[90:91], v[108:109], v[60:61] neg_lo:[0,0,1] neg_hi:[0,0,1]
	v_pk_mul_f32 v[64:65], v[84:85], v[68:69]
	v_pk_fma_f32 v[68:69], v[88:89], v[106:107], v[54:55] neg_lo:[0,0,1] neg_hi:[0,0,1]
	v_cvt_pk_bf16_f32 v55, v60, v61
	v_lshlrev_b64 v[60:61], 10, v[52:53]
	v_pk_mul_f32 v[56:57], v[72:73], v[56:57]
	v_lshl_add_u64 v[60:61], s[24:25], 0, v[60:61]
	v_pk_fma_f32 v[56:57], v[86:87], v[104:105], v[56:57] neg_lo:[0,0,1] neg_hi:[0,0,1]
	v_pk_fma_f32 v[64:65], v[92:93], v[110:111], v[64:65] neg_lo:[0,0,1] neg_hi:[0,0,1]
	v_lshl_add_u64 v[60:61], s[10:11], 1, v[60:61]
	v_pk_fma_f32 v[62:63], v[78:79], v[96:97], v[62:63]
	v_pk_fma_f32 v[58:59], v[82:83], v[100:101], v[58:59]
	v_cvt_pk_bf16_f32 v54, v56, v57
	v_cvt_pk_bf16_f32 v56, v68, v69
	v_cvt_pk_bf16_f32 v57, v64, v65
	v_lshl_add_u64 v[60:61], v[60:61], 0, v[152:153]
	global_store_dwordx4 v[60:61], v[54:57], off
	s_nop 1
	v_cvt_pk_bf16_f32 v54, v66, v67
	v_cvt_pk_bf16_f32 v55, v62, v63
	v_cvt_pk_bf16_f32 v56, v70, v71
	v_cvt_pk_bf16_f32 v57, v58, v59
	global_store_dwordx4 v[60:61], v[54:57], off offset:64

.LBB0_1513:
	s_nop 1
	v_add_u32_e32 v36, 0xa0, v154
	v_ashrrev_i32_e32 v37, 31, v36
	s_and_b64 vcc, exec, s[6:7]
	s_mov_b64 s[52:53], -1
	v_fmamk_f32 v34, v237, 0x3aaaaaab, v160
	v_rsq_f32_e32 v34, v34
	s_nop 0
	v_mul_f32_e32 v34, 0x3dd53b94, v34
	s_cbranch_vccnz .LBB0_1515
	v_lshlrev_b32_e32 v35, 5, v36
	v_and_or_b32 v35, v35, s72, v140
	v_lshlrev_b32_e32 v35, 3, v35
	global_load_dwordx4 v[38:41], v35, s[26:27]
	global_load_dwordx4 v[42:45], v35, s[26:27] offset:16
	global_load_dwordx4 v[46:49], v35, s[26:27] offset:32
	global_load_dwordx4 v[50:53], v35, s[26:27] offset:48
	v_mov_b32_e32 v62, v32
	v_mov_b32_e32 v63, v25
	v_mov_b32_e32 v64, v24
	v_mov_b32_e32 v65, v33
	v_mov_b32_e32 v56, v22
	v_mov_b32_e32 v57, v31
	v_mov_b32_e32 v58, v26
	v_mov_b32_e32 v59, v19
	v_mov_b32_e32 v60, v18
	v_mov_b32_e32 v61, v27
	v_pk_mul_f32 v[62:63], v[62:63], v[34:35] op_sel_hi:[1,0]
	v_pk_mul_f32 v[64:65], v[64:65], v[34:35] op_sel_hi:[1,0]
	v_mov_b32_e32 v54, v30
	v_mov_b32_e32 v55, v23
	v_mov_b32_e32 v66, v28
	v_mov_b32_e32 v67, v21
	v_mov_b32_e32 v68, v20
	v_mov_b32_e32 v69, v29
	v_pk_mul_f32 v[56:57], v[56:57], v[34:35] op_sel_hi:[1,0]
	v_pk_mul_f32 v[58:59], v[58:59], v[34:35] op_sel_hi:[1,0]
	v_pk_mul_f32 v[60:61], v[60:61], v[34:35] op_sel_hi:[1,0]
	v_mov_b32_e32 v75, v65
	v_pk_mul_f32 v[54:55], v[54:55], v[34:35] op_sel_hi:[1,0]
	v_pk_mul_f32 v[66:67], v[66:67], v[34:35] op_sel_hi:[1,0]
	v_pk_mul_f32 v[68:69], v[68:69], v[34:35] op_sel_hi:[1,0]
	v_mov_b32_e32 v73, v61
	v_mov_b32_e32 v74, v62
	v_mov_b32_e32 v70, v54
	v_mov_b32_e32 v71, v57
	v_mov_b32_e32 v72, v58
	v_mov_b32_e32 v77, v69
	v_mov_b32_e32 v76, v66
	v_mov_b32_e32 v153, v139
	s_mov_b64 s[52:53], 0
	s_waitcnt vmcnt(3)
	v_mov_b32_e32 v86, v38
	v_mov_b32_e32 v88, v38
	s_waitcnt vmcnt(1)
	v_mov_b32_e32 v82, v47
	v_mov_b32_e32 v83, v48
	v_mov_b32_e32 v38, v46
	v_mov_b32_e32 v90, v46
	v_mov_b32_e32 v91, v48
	v_mov_b32_e32 v48, v47
	v_mov_b32_e32 v46, v42
	v_mov_b32_e32 v47, v45
	v_mov_b32_e32 v78, v39
	v_mov_b32_e32 v79, v40
	v_mov_b32_e32 v81, v44
	v_mov_b32_e32 v87, v41
	v_mov_b32_e32 v89, v40
	v_mov_b32_e32 v40, v39
	v_mov_b32_e32 v39, v49
	v_mov_b32_e32 v93, v44
	v_mov_b32_e32 v44, v43
	v_pk_mul_f32 v[46:47], v[64:65], v[46:47]
	v_mov_b32_e32 v65, v63
	v_mov_b32_e32 v80, v43
	s_waitcnt vmcnt(0)
	v_mov_b32_e32 v84, v51
	v_mov_b32_e32 v85, v52
	v_mov_b32_e32 v92, v42
	v_mov_b32_e32 v42, v50
	v_mov_b32_e32 v43, v53
	v_mov_b32_e32 v94, v50
	v_mov_b32_e32 v95, v52
	v_mov_b32_e32 v52, v51
	v_pk_mul_f32 v[50:51], v[56:57], v[86:87]
	v_pk_mul_f32 v[38:39], v[60:61], v[38:39]
	v_mov_b32_e32 v61, v59
	v_pk_mul_f32 v[44:45], v[64:65], v[44:45]
	v_mov_b32_e32 v57, v55
	v_pk_mul_f32 v[42:43], v[68:69], v[42:43]
	v_mov_b32_e32 v69, v67
	v_pk_fma_f32 v[50:51], v[54:55], v[78:79], v[50:51]
	v_pk_fma_f32 v[54:55], v[58:59], v[82:83], v[38:39]
	v_pk_mul_f32 v[38:39], v[60:61], v[48:49]
	v_pk_fma_f32 v[44:45], v[74:75], v[92:93], v[44:45] neg_lo:[0,0,1] neg_hi:[0,0,1]
	v_pk_mul_f32 v[48:49], v[68:69], v[52:53]
	v_pk_fma_f32 v[52:53], v[72:73], v[90:91], v[38:39] neg_lo:[0,0,1] neg_hi:[0,0,1]
	v_cvt_pk_bf16_f32 v39, v44, v45
	v_lshlrev_b64 v[44:45], 10, v[36:37]
	v_pk_mul_f32 v[40:41], v[56:57], v[40:41]
	v_lshl_add_u64 v[44:45], s[24:25], 0, v[44:45]
	v_pk_fma_f32 v[40:41], v[70:71], v[88:89], v[40:41] neg_lo:[0,0,1] neg_hi:[0,0,1]
	v_pk_fma_f32 v[48:49], v[76:77], v[94:95], v[48:49] neg_lo:[0,0,1] neg_hi:[0,0,1]
	v_lshl_add_u64 v[44:45], s[10:11], 1, v[44:45]
	v_pk_fma_f32 v[46:47], v[62:63], v[80:81], v[46:47]
	v_pk_fma_f32 v[42:43], v[66:67], v[84:85], v[42:43]
	v_cvt_pk_bf16_f32 v38, v40, v41
	v_cvt_pk_bf16_f32 v40, v52, v53
	v_cvt_pk_bf16_f32 v41, v48, v49
	v_lshl_add_u64 v[44:45], v[44:45], 0, v[152:153]
	global_store_dwordx4 v[44:45], v[38:41], off
	s_nop 1
	v_cvt_pk_bf16_f32 v38, v50, v51
	v_cvt_pk_bf16_f32 v39, v46, v47
	v_cvt_pk_bf16_f32 v40, v54, v55
	v_cvt_pk_bf16_f32 v41, v42, v43
	global_store_dwordx4 v[44:45], v[38:41], off offset:64

.LBB0_1517:
	s_nop 1
	v_add_u32_e32 v20, 0xb0, v154
	v_ashrrev_i32_e32 v21, 31, v20
	s_and_b64 vcc, exec, s[6:7]
	s_mov_b64 s[6:7], -1
	v_fmamk_f32 v18, v238, 0x3aaaaaab, v160
	v_rsq_f32_e32 v18, v18
	s_nop 0
	v_mul_f32_e32 v18, 0x3dd53b94, v18
	s_cbranch_vccz .LBB0_1520
	s_andn2_b64 vcc, exec, s[6:7]
	s_cbranch_vccz .LBB0_1521
